# v026 + QKV epilogue (P1/P3): the 8 stores of the second accumulator half (row groups 4-7, registers not touched by the next tile's first MFMA block) are issued inside the next tile's peeled first MFMA
# speedup vs baseline: 1.0004x; 1.0004x over previous
; #define PG8_STAGE(bufoff, gbase, voff) do { _Pragma("unroll") for (int _i = 0; _i < 2; ++_i) \
;         __builtin_amdgcn_global_load_lds((const unsigned*)((const char*)(gbase) + (voff)[_i]), (PG8_LAS unsigned*)(lds + (bufoff) + ldsw + _i * 8192), 16, 0, PG8_LOAD_AUX); } while (0)
; #define PG8_LDA(dst, b, h) do { _Pragma("unroll") for (int m = 0; m < 4; ++m) _Pragma("unroll") for (int k = 0; k < 2; ++k) dst[m][k] = *(const PG8_LAS bf16x8*)(lds + PG8_SA(b, h) + aoff + m * 2048 + k * 1024); } while (0)
; #define PG8_LDB(dst, b, h) do { _Pragma("unroll") for (int n = 0; n < 2; ++n) _Pragma("unroll") for (int k = 0; k < 2; ++k) dst[n][k] = *(const PG8_LAS bf16x8*)(lds + PG8_SB(b, h) + boff + n * 2048 + k * 1024); } while (0)
; template <class Epi, class Sched, bool ALIGN_EPI = false, bool SP2 = false>
; __device__ __forceinline__ void gemm_phase(PG8_LAS unsigned char* lds, const Gemm g, const Sched& S, const Epi& E) {
;     ...
;         PG8_STAGE(PG8_SB(1, 0), cB + kstep, voffB); PG8_STAGE(PG8_SA(1, 0), cA + kstep, voffA); PG8_STAGE(PG8_SB(1, 1), cB + hstepB + kstep, voffB);
;         PG8_WAIT_V(6); PG8_BAR;
;     } else {
;         PG8_STAGE(PG8_SB(0, 0), cB, voffB); PG8_STAGE(PG8_SA(0, 0), cA, voffA); PG8_STAGE(PG8_SB(0, 1), cB + hstepB, voffB); PG8_STAGE(PG8_SA(0, 1), cA + hstepA, voffA);
;         if (wr == 1) PG8_BAR;
;         PG8_WAIT_V(4); PG8_BAR;
;         PG8_STAGE(PG8_SB(1, 0), cB + kstep, voffB); PG8_STAGE(PG8_SA(1, 0), cA + kstep, voffA); PG8_STAGE(PG8_SB(1, 1), cB + hstepB + kstep, voffB);
;         PG8_WAIT_V(6); PG8_BAR;
;     }
;     for (;;) {
;         const bool has_next = S.next(ui + 1, nxt);
;         const char* nA = has_next ? (const char*)g.A + (size_t)nxt.pm * tstepA + (size_t)nxt.pn * apn : cA; const char* nB = has_next ? (const char*)g.Bt + (size_t)nxt.pn * tstepB : cB;
;         for (int t = 0; t < nt; t += 2) {
;             const bool last = (t == nt - 2);
;             const char* a1 = cA + (size_t)(t + 1) * kstep;
;             const char* a2 = last ? nA : cA + (size_t)(t + 2) * kstep; const char* b2 = last ? nB : cB + (size_t)(t + 2) * kstep;
;             const char* a3 = a2 + kstep; const char* b3 = b2 + kstep;
;             if (last && has_next) S.a_ready(nxt);
;             if constexpr (SP2) {
;             PG8_LDB(B0, 0, 0); PG8_LDB(B1, 0, 1); PG8_SCHED; PG8_LDA(At, 0, 0); PG8_STAGE(PG8_SA(1, 1), a1 + hstepA, voffA);
.LBB0_209:
	s_mov_b64 s[10:11], 0x80
	s_and_b32 s14, s3, 3
	s_add_i32 m0, s42, 0x18000
	v_lshl_add_u64 v[6:7], v[6:7], 0, s[10:11]
	s_ashr_i32 s47, s86, 31
	s_lshl_b32 s15, s5, 13
	s_lshl_b32 s16, s14, 12
	global_load_lds_dwordx4 v[6:7], off
	v_lshl_add_u64 v[4:5], v[4:5], 0, s[10:11]
	s_add_i32 m0, s42, 0x1a000
	s_add_i32 s48, s42, 0x8000
	s_add_i32 s49, s42, 0xa000
	global_load_lds_dwordx4 v[4:5], off
	v_lshl_add_u64 v[0:1], v[0:1], 0, s[10:11]
	s_mov_b32 m0, s48
	s_add_u32 s12, s22, 0x10080
	global_load_lds_dwordx4 v[0:1], off
	v_lshl_add_u64 v[0:1], v[2:3], 0, s[10:11]
	s_mov_b32 m0, s49
	s_addc_u32 s13, s23, 0
	global_load_lds_dwordx4 v[0:1], off
	s_add_i32 m0, s42, 0x1c000
	v_lshl_add_u64 v[0:1], s[12:13], 0, v[130:131]
	global_load_lds_dwordx4 v[0:1], off
	v_lshl_add_u64 v[0:1], s[12:13], 0, v[134:135]
	s_add_i32 m0, s42, 0x1e000
	s_sext_i32_i16 s1, s2
	global_load_lds_dwordx4 v[0:1], off
	s_waitcnt vmcnt(8)
	s_barrier
	v_bfe_u32 v0, v154, 4, 2
	v_lshlrev_b32_e32 v2, 3, v0
	v_and_b32_e32 v1, 15, v154
	v_lshlrev_b32_e32 v3, 4, v0
	v_lshlrev_b32_e32 v0, 6, v154
	s_movk_i32 s2, 0x3c0
	v_lshl_or_b32 v147, s14, 6, v2
	v_lshlrev_b32_e32 v2, 8, v154
	v_and_or_b32 v4, v0, s2, v3
	v_cmp_gt_u32_e64 s[2:3], 8, v1
	v_lshl_or_b32 v1, v1, 6, v3
	v_and_b32_e32 v2, 0x38000, v2
	v_lshlrev_b32_e32 v3, 11, v10
	v_or3_b32 v2, v8, v2, v3
	v_lshlrev_b32_e32 v0, 2, v154
	v_add_u32_e32 v138, v2, v9
	v_lshlrev_b32_e32 v2, 4, v11
	v_and_b32_e32 v5, 32, v0
	v_and_b32_e32 v6, 7, v154
	s_waitcnt vmcnt(6)
	s_cmpk_lt_u32 s4, 0x100
	v_and_b32_e32 v2, 0x78000, v2
	v_cndmask_b32_e64 v0, 32, 0, s[2:3]
	v_bitop3_b32 v1, v1, s15, v5 bitop3:0xde
	v_bitop3_b32 v146, s16, v4, v5 bitop3:0xf6
	s_cselect_b64 s[12:13], -1, 0
	v_lshl_or_b32 v148, s5, 6, v6
	v_or3_b32 v2, v8, v2, v3
	s_add_i32 s51, 0, 0x10000
	s_add_i32 s52, 0, 0x14000
	s_mov_b32 s50, s86
	v_or_b32_e32 v149, 16, v148
	v_or_b32_e32 v150, 32, v148
	v_or_b32_e32 v151, 48, v148
	v_add_u32_e32 v152, 0x80, v148
	v_add_u32_e32 v155, 0x90, v148
	v_add_u32_e32 v156, 0xa0, v148
	v_add_u32_e32 v157, 0xb0, v148
	v_mov_b32_e32 v139, v137
	v_add_u32_e32 v140, v2, v9
	v_mov_b32_e32 v141, v137
	v_mov_b64_e32 v[142:143], 0x900
	v_mov_b64_e32 v[144:145], 0x8ff
	v_add_u32_e32 v158, s51, v146
	v_add_u32_e32 v159, s52, v146
	v_add_u32_e32 v160, 0, v1
	s_movk_i32 s53, 0x4800
	v_lshlrev_b32_e32 v136, 1, v0
	s_mov_b32 s54, 0x24000
	s_barrier
	s_add_u32 s20, s20, 0x40080
	s_addc_u32 s21, s21, 0
	s_add_u32 s26, s22, 0x100
	s_addc_u32 s27, s23, 0
	s_mov_b32 s28, -2
	ds_read_b128 v[162:165], v158
	ds_read_b128 v[166:169], v158 offset:1024
	ds_read_b128 v[170:173], v158 offset:2048
	ds_read_b128 v[174:177], v158 offset:3072
	ds_read_b128 v[178:181], v159
	ds_read_b128 v[182:185], v159 offset:1024
	ds_read_b128 v[186:189], v159 offset:2048
	ds_read_b128 v[190:193], v159 offset:3072
	s_add_u32 s22, s20, 0xfffc0080
	s_addc_u32 s23, s21, -1
	s_cmp_eq_u32 s28, 12
	s_cselect_b32 s35, s17, s23
	s_cselect_b32 s34, s24, s22
	s_cselect_b32 s23, s15, s27
	s_cselect_b32 s22, s25, s26
	v_lshl_add_u64 v[226:227], s[20:21], 0, v[138:139]
	s_add_i32 m0, s42, 0xc000
	ds_read_b128 v[194:197], v160
	ds_read_b128 v[198:201], v160 offset:1024
	ds_read_b128 v[202:205], v160 offset:2048
	ds_read_b128 v[206:209], v160 offset:3072
	ds_read_b128 v[210:213], v160 offset:4096
	ds_read_b128 v[214:217], v160 offset:5120
	ds_read_b128 v[218:221], v160 offset:6144
	ds_read_b128 v[222:225], v160 offset:7168
	global_load_lds_dwordx4 v[226:227], off
	v_lshl_add_u64 v[226:227], s[20:21], 0, v[140:141]
	s_add_i32 m0, s42, 0xe000
	s_nop 0
	global_load_lds_dwordx4 v[226:227], off
	s_waitcnt vmcnt(8)
	s_waitcnt lgkmcnt(0)
	s_barrier
; #define PG8_STAGE(bufoff, gbase, voff) do { _Pragma("unroll") for (int _i = 0; _i < 2; ++_i) \
;         __builtin_amdgcn_global_load_lds((const unsigned*)((const char*)(gbase) + (voff)[_i]), (PG8_LAS unsigned*)(lds + (bufoff) + ldsw + _i * 8192), 16, 0, PG8_LOAD_AUX); } while (0)
; #define PG8_LDA(dst, b, h) do { _Pragma("unroll") for (int m = 0; m < 4; ++m) _Pragma("unroll") for (int k = 0; k < 2; ++k) dst[m][k] = *(const PG8_LAS bf16x8*)(lds + PG8_SA(b, h) + aoff + m * 2048 + k * 1024); } while (0)
; #define PG8_LDB(dst, b, h) do { _Pragma("unroll") for (int n = 0; n < 2; ++n) _Pragma("unroll") for (int k = 0; k < 2; ++k) dst[n][k] = *(const PG8_LAS bf16x8*)(lds + PG8_SB(b, h) + boff + n * 2048 + k * 1024); } while (0)
; #define PG8_WAIT_V(n) asm volatile("s_waitcnt vmcnt(" #n ")" ::: "memory")
; #define PG8_WAIT_L(n) asm volatile("s_waitcnt lgkmcnt(" #n ")" ::: "memory")
; #define PG8_BAR __builtin_amdgcn_s_barrier()
; #define PG8_SCHED __builtin_amdgcn_sched_barrier(0)
; template <class Epi, class Sched, bool ALIGN_EPI = false, bool SP2 = false>
; __device__ __forceinline__ void gemm_phase(PG8_LAS unsigned char* lds, const Gemm g, const Sched& S, const Epi& E) {
;     ...
;         const bool has_next = S.next(ui + 1, nxt);
;         const char* nA = has_next ? (const char*)g.A + (size_t)nxt.pm * tstepA + (size_t)nxt.pn * apn : cA; const char* nB = has_next ? (const char*)g.Bt + (size_t)nxt.pn * tstepB : cB;
;         for (int t = 0; t < nt; t += 2) {
;             const bool last = (t == nt - 2);
;             const char* a1 = cA + (size_t)(t + 1) * kstep;
;             const char* a2 = last ? nA : cA + (size_t)(t + 2) * kstep; const char* b2 = last ? nB : cB + (size_t)(t + 2) * kstep;
;             const char* a3 = a2 + kstep; const char* b3 = b2 + kstep;
;             if (last && has_next) S.a_ready(nxt);
;             if constexpr (SP2) {
;             PG8_LDB(B0, 0, 0); PG8_LDB(B1, 0, 1); PG8_SCHED; PG8_LDA(At, 0, 0); PG8_STAGE(PG8_SA(1, 1), a1 + hstepA, voffA);
;             PG8_WAIT_V(8); PG8_WAIT_L(0); PG8_BAR; PG8_MMA(0, 0, At, B0); PG8_MMA(0, 1, At, B1); PG8_BAR; PG8_SCHED;
;             PG8_LDA(At, 0, 1); PG8_STAGE(PG8_SB(0, 0), b2, voffB); PG8_STAGE(PG8_SB(0, 1), b2 + hstepB, voffB); PG8_STAGE(PG8_SA(0, 0), a2, voffA);
;             PG8_WAIT_V(8); PG8_WAIT_L(0); PG8_BAR; PG8_MMA(1, 0, At, B0); PG8_MMA(1, 1, At, B1); PG8_BAR; PG8_SCHED;
	s_waitcnt lgkmcnt(0)
	v_mfma_f32_16x16x32_bf16 v[124:127], v[162:165], v[194:197], 0
	s_add_i32 s46, s46, 1
	s_mul_i32 s4, s46, s47
	v_mfma_f32_16x16x32_bf16 v[120:123], v[170:173], v[194:197], 0
	s_mul_hi_u32 s5, s46, s50
	s_add_i32 s5, s5, s4
	v_mfma_f32_16x16x32_bf16 v[108:111], v[162:165], v[202:205], 0
	s_mul_i32 s4, s46, s50
	v_readlane_b32 s15, v239, 0
	v_mfma_f32_16x16x32_bf16 v[104:107], v[170:173], v[202:205], 0
	s_add_u32 s18, s4, s15
	s_addc_u32 s19, s5, s36
	v_mfma_f32_16x16x32_bf16 v[92:95], v[162:165], v[210:213], 0
	s_cmp_lt_u32 s18, 0x900
	s_cselect_b64 s[4:5], -1, 0
	v_mfma_f32_16x16x32_bf16 v[88:91], v[170:173], v[210:213], 0
	s_ashr_i32 s14, s18, 31
	s_lshr_b32 s14, s14, 29
	v_mfma_f32_16x16x32_bf16 v[76:79], v[162:165], v[218:221], 0
	s_add_i32 s14, s18, s14
	s_ashr_i32 s15, s14, 3
	v_mfma_f32_16x16x32_bf16 v[72:75], v[170:173], v[218:221], 0
	s_and_b32 s14, s14, -8
	s_sub_i32 s14, s18, s14
	v_mfma_f32_16x16x32_bf16 v[124:127], v[166:169], v[198:201], v[124:127]
	s_cmp_lt_i32 s14, 0
	s_cselect_b32 s16, s37, 0x120
	v_mfma_f32_16x16x32_bf16 v[120:123], v[174:177], v[198:201], v[120:123]
	s_mul_i32 s14, s14, s16
	s_add_i32 s14, s14, s15
	v_mfma_f32_16x16x32_bf16 v[108:111], v[166:169], v[206:209], v[108:111]
	s_mul_hi_i32 s15, s14, 0x38e38e39
	s_lshr_b32 s16, s15, 31
	v_mfma_f32_16x16x32_bf16 v[104:107], v[174:177], v[206:209], v[104:107]
	s_ashr_i32 s15, s15, 5
	s_add_i32 s15, s15, s16
	v_mfma_f32_16x16x32_bf16 v[92:95], v[166:169], v[214:217], v[92:95]
	s_lshl_b32 s16, s15, 2
	s_sub_i32 s17, 64, s16
	v_mfma_f32_16x16x32_bf16 v[88:91], v[174:177], v[214:217], v[88:91]
	s_min_i32 s17, s17, 4
	s_mulk_i32 s15, 0x90
	v_mfma_f32_16x16x32_bf16 v[76:79], v[166:169], v[222:225], v[76:79]
	s_sub_i32 s15, s14, s15
	s_lshr_b32 s14, s15, 2
	v_mfma_f32_16x16x32_bf16 v[72:75], v[174:177], v[222:225], v[72:75]
	s_and_b32 s15, s15, 3
	s_add_i32 s16, s16, s15
	v_mfma_f32_16x16x32_bf16 v[116:119], v[178:181], v[194:197], 0
	s_ashr_i32 s17, s16, 31
	s_lshl_b64 s[18:19], s[16:17], 19
	v_mfma_f32_16x16x32_bf16 v[112:115], v[186:189], v[194:197], 0
	v_readlane_b32 s24, v239, 47
	v_readlane_b32 s25, v239, 48
	v_mfma_f32_16x16x32_bf16 v[100:103], v[178:181], v[202:205], 0
	s_add_u32 s18, s24, s18
	s_addc_u32 s19, s25, s19
	v_mfma_f32_16x16x32_bf16 v[96:99], v[186:189], v[202:205], 0
	s_sub_u32 s98, s20, 0x40080
	s_subb_u32 s99, s21, 0
	v_mfma_f32_16x16x32_bf16 v[84:87], v[178:181], v[210:213], 0
	s_cmp_lg_u64 s[4:5], 0
	s_cselect_b32 s17, s19, s99
	v_mfma_f32_16x16x32_bf16 v[80:83], v[186:189], v[210:213], 0
	s_cselect_b32 s24, s18, s98
	s_ashr_i32 s15, s14, 31
	v_mfma_f32_16x16x32_bf16 v[68:71], v[178:181], v[218:221], 0
	s_lshl_b64 s[98:99], s[14:15], 19
	s_add_u32 s40, s64, s98
	v_mfma_f32_16x16x32_bf16 v[64:67], v[186:189], v[218:221], 0
	s_addc_u32 s41, s65, s99
	s_sub_u32 s98, s26, 0x100
	v_mfma_f32_16x16x32_bf16 v[116:119], v[182:185], v[198:201], v[116:119]
	s_subb_u32 s99, s27, 0
	s_cmp_lg_u64 s[4:5], 0
	v_mfma_f32_16x16x32_bf16 v[112:115], v[190:193], v[198:201], v[112:115]
	s_cselect_b32 s15, s41, s99
	s_cselect_b32 s25, s40, s98
	v_mfma_f32_16x16x32_bf16 v[100:103], v[182:185], v[206:209], v[100:103]
	v_mfma_f32_16x16x32_bf16 v[96:99], v[190:193], v[206:209], v[96:99]
	v_mfma_f32_16x16x32_bf16 v[84:87], v[182:185], v[214:217], v[84:87]
	v_mfma_f32_16x16x32_bf16 v[80:83], v[190:193], v[214:217], v[80:83]
	v_mfma_f32_16x16x32_bf16 v[68:71], v[182:185], v[222:225], v[68:71]
	v_mfma_f32_16x16x32_bf16 v[64:67], v[190:193], v[222:225], v[64:67]
	s_barrier
	s_add_i32 s29, s51, s33
	v_lshl_add_u64 v[226:227], s[22:23], 0, v[130:131]
	s_mov_b32 m0, s29
	ds_read_b128 v[194:197], v160 offset:16384
	ds_read_b128 v[198:201], v160 offset:17408
	ds_read_b128 v[202:205], v160 offset:18432
	ds_read_b128 v[206:209], v160 offset:19456
	ds_read_b128 v[210:213], v160 offset:20480
	ds_read_b128 v[214:217], v160 offset:21504
	ds_read_b128 v[218:221], v160 offset:22528
	ds_read_b128 v[222:225], v160 offset:23552
	global_load_lds_dwordx4 v[226:227], off
	s_add_i32 m0, s29, 0x2000
	s_add_u32 s30, s22, 0x10000
	v_lshl_add_u64 v[228:229], s[22:23], 0, v[134:135]
	s_addc_u32 s31, s23, 0
	s_add_i32 s29, s52, s33
	global_load_lds_dwordx4 v[228:229], off
	v_lshl_add_u64 v[230:231], s[30:31], 0, v[130:131]
	s_mov_b32 m0, s29
	v_lshl_add_u64 v[232:233], s[34:35], 0, v[132:133]
	global_load_lds_dwordx4 v[230:231], off
	v_lshl_add_u64 v[230:231], s[30:31], 0, v[134:135]
	s_add_i32 m0, s29, 0x2000
	s_nop 0
	global_load_lds_dwordx4 v[230:231], off
	v_lshl_add_u64 v[230:231], s[34:35], 0, v[128:129]
	s_mov_b32 m0, s42
	s_nop 0
	global_load_lds_dwordx4 v[230:231], off
	s_mov_b32 m0, s43
	s_nop 0
	global_load_lds_dwordx4 v[232:233], off
	s_waitcnt vmcnt(8)
	s_waitcnt lgkmcnt(0)
	s_barrier
	s_waitcnt lgkmcnt(0)
	v_mfma_f32_16x16x32_bf16 v[60:63], v[162:165], v[194:197], 0
	v_mfma_f32_16x16x32_bf16 v[56:59], v[170:173], v[194:197], 0
	v_mfma_f32_16x16x32_bf16 v[44:47], v[162:165], v[202:205], 0
	v_mfma_f32_16x16x32_bf16 v[40:43], v[170:173], v[202:205], 0
	v_mfma_f32_16x16x32_bf16 v[28:31], v[162:165], v[210:213], 0
	v_mfma_f32_16x16x32_bf16 v[24:27], v[170:173], v[210:213], 0
	v_mfma_f32_16x16x32_bf16 v[12:15], v[162:165], v[218:221], 0
	v_mfma_f32_16x16x32_bf16 v[8:11], v[170:173], v[218:221], 0
	v_mfma_f32_16x16x32_bf16 v[60:63], v[166:169], v[198:201], v[60:63]
	v_mfma_f32_16x16x32_bf16 v[56:59], v[174:177], v[198:201], v[56:59]
	v_mfma_f32_16x16x32_bf16 v[44:47], v[166:169], v[206:209], v[44:47]
	v_mfma_f32_16x16x32_bf16 v[40:43], v[174:177], v[206:209], v[40:43]
	v_mfma_f32_16x16x32_bf16 v[28:31], v[166:169], v[214:217], v[28:31]
	v_mfma_f32_16x16x32_bf16 v[24:27], v[174:177], v[214:217], v[24:27]
	v_mfma_f32_16x16x32_bf16 v[12:15], v[166:169], v[222:225], v[12:15]
	v_mfma_f32_16x16x32_bf16 v[8:11], v[174:177], v[222:225], v[8:11]
	v_mfma_f32_16x16x32_bf16 v[52:55], v[178:181], v[194:197], 0
	v_mfma_f32_16x16x32_bf16 v[48:51], v[186:189], v[194:197], 0
	v_mfma_f32_16x16x32_bf16 v[36:39], v[178:181], v[202:205], 0
	v_mfma_f32_16x16x32_bf16 v[32:35], v[186:189], v[202:205], 0
	v_mfma_f32_16x16x32_bf16 v[20:23], v[178:181], v[210:213], 0
	v_mfma_f32_16x16x32_bf16 v[16:19], v[186:189], v[210:213], 0
	v_mfma_f32_16x16x32_bf16 v[4:7], v[178:181], v[218:221], 0
	v_mfma_f32_16x16x32_bf16 v[0:3], v[186:189], v[218:221], 0
	v_mfma_f32_16x16x32_bf16 v[52:55], v[182:185], v[198:201], v[52:55]
	v_mfma_f32_16x16x32_bf16 v[48:51], v[190:193], v[198:201], v[48:51]
	v_mfma_f32_16x16x32_bf16 v[36:39], v[182:185], v[206:209], v[36:39]
	v_mfma_f32_16x16x32_bf16 v[32:35], v[190:193], v[206:209], v[32:35]
	v_mfma_f32_16x16x32_bf16 v[20:23], v[182:185], v[214:217], v[20:23]
	v_mfma_f32_16x16x32_bf16 v[16:19], v[190:193], v[214:217], v[16:19]
	v_mfma_f32_16x16x32_bf16 v[4:7], v[182:185], v[222:225], v[4:7]
	v_mfma_f32_16x16x32_bf16 v[0:3], v[190:193], v[222:225], v[0:3]
	s_barrier
	s_branch .Lkmid_P1

; __device__ __forceinline__ unsigned swap8(unsigned v) { return (unsigned)__builtin_amdgcn_update_dpp(0, (int)v, 0x128  , 0xF, 0xF, false); }
; #define PG8_STAGE(bufoff, gbase, voff) do { _Pragma("unroll") for (int _i = 0; _i < 2; ++_i) \
;         __builtin_amdgcn_global_load_lds((const unsigned*)((const char*)(gbase) + (voff)[_i]), (PG8_LAS unsigned*)(lds + (bufoff) + ldsw + _i * 8192), 16, 0, PG8_LOAD_AUX); } while (0)
; #define PG8_LDA(dst, b, h) do { _Pragma("unroll") for (int m = 0; m < 4; ++m) _Pragma("unroll") for (int k = 0; k < 2; ++k) dst[m][k] = *(const PG8_LAS bf16x8*)(lds + PG8_SA(b, h) + aoff + m * 2048 + k * 1024); } while (0)
; #define PG8_BAR __builtin_amdgcn_s_barrier()
; __device__ __forceinline__ void wide_store(bf16_t* O, int ldc, int rowg  , int col0  , int fr, u32x4 w0, u32x4 w1) {
;     const bool lo = fr < 8;
;     u32x4 snd = lo ? w1 : w0, rcv;
;     rcv.x = swap8(snd.x); rcv.y = swap8(snd.y); rcv.z = swap8(snd.z); rcv.w = swap8(snd.w);
;     const u32x4 first = lo ? w0 : rcv, second = lo ? rcv : w1;
;     bf16_t* p = O + (size_t)(rowg + (fr & 7)) * ldc + col0 + (lo ? 0 : 32);
;     __builtin_nontemporal_store(first, (u32x4*)p); __builtin_nontemporal_store(second, (u32x4*)(p + (size_t)8 * ldc));
; }
; template <class Epi, class Sched, bool ALIGN_EPI = false, bool SP2 = false>
; __device__ __forceinline__ void gemm_phase(PG8_LAS unsigned char* lds, const Gemm g, const Sched& S, const Epi& E) {
;     ...
;         const bool has_next = S.next(ui + 1, nxt);
;         const char* nA = has_next ? (const char*)g.A + (size_t)nxt.pm * tstepA + (size_t)nxt.pn * apn : cA; const char* nB = has_next ? (const char*)g.Bt + (size_t)nxt.pn * tstepB : cB;
;         for (int t = 0; t < nt; t += 2) {
;             const bool last = (t == nt - 2);
;             const char* a1 = cA + (size_t)(t + 1) * kstep;
;             const char* a2 = last ? nA : cA + (size_t)(t + 2) * kstep; const char* b2 = last ? nB : cB + (size_t)(t + 2) * kstep;
;             const char* a3 = a2 + kstep; const char* b3 = b2 + kstep;
;             if (last && has_next) S.a_ready(nxt);
;             if constexpr (SP2) {
;             PG8_LDB(B0, 0, 0); PG8_LDB(B1, 0, 1); PG8_SCHED; PG8_LDA(At, 0, 0); PG8_STAGE(PG8_SA(1, 1), a1 + hstepA, voffA);
;             PG8_WAIT_V(8); PG8_WAIT_L(0); PG8_BAR; PG8_MMA(0, 0, At, B0); PG8_MMA(0, 1, At, B1); PG8_BAR; PG8_SCHED;
.LBB0_212:
	s_add_u32 s20, s20, 0x40080
	s_addc_u32 s21, s21, 0
	s_add_u32 s26, s22, 0x100
	s_addc_u32 s27, s23, 0
	s_mov_b32 s28, -2
	ds_read_b128 v[162:165], v158
	ds_read_b128 v[166:169], v158 offset:1024
	ds_read_b128 v[170:173], v158 offset:2048
	ds_read_b128 v[174:177], v158 offset:3072
	ds_read_b128 v[178:181], v159
	ds_read_b128 v[182:185], v159 offset:1024
	ds_read_b128 v[186:189], v159 offset:2048
	ds_read_b128 v[190:193], v159 offset:3072
	s_add_u32 s22, s20, 0xfffc0080
	s_addc_u32 s23, s21, -1
	s_cmp_eq_u32 s28, 12
	s_cselect_b32 s35, s17, s23
	s_cselect_b32 s34, s24, s22
	s_cselect_b32 s23, s15, s27
	s_cselect_b32 s22, s25, s26
	v_lshl_add_u64 v[226:227], s[20:21], 0, v[138:139]
	s_add_i32 m0, s42, 0xc000
	ds_read_b128 v[194:197], v160
	ds_read_b128 v[198:201], v160 offset:1024
	ds_read_b128 v[202:205], v160 offset:2048
	ds_read_b128 v[206:209], v160 offset:3072
	ds_read_b128 v[210:213], v160 offset:4096
	ds_read_b128 v[214:217], v160 offset:5120
	ds_read_b128 v[218:221], v160 offset:6144
	ds_read_b128 v[222:225], v160 offset:7168
	global_load_lds_dwordx4 v[226:227], off
	v_lshl_add_u64 v[226:227], s[20:21], 0, v[140:141]
	s_add_i32 m0, s42, 0xe000
	s_nop 0
	global_load_lds_dwordx4 v[226:227], off
	s_waitcnt vmcnt(8)
	s_waitcnt lgkmcnt(0)
	s_barrier
	s_waitcnt lgkmcnt(0)
	v_mfma_f32_16x16x32_bf16 v[124:127], v[162:165], v[194:197], 0
	s_add_i32 s46, s46, 1
	s_mul_i32 s4, s46, s47
	v_mfma_f32_16x16x32_bf16 v[120:123], v[170:173], v[194:197], 0
	s_mul_hi_u32 s5, s46, s50
	s_add_i32 s5, s5, s4
	v_mfma_f32_16x16x32_bf16 v[108:111], v[162:165], v[202:205], 0
	global_store_dwordx4 v[240:241], v[56:59], off nt
	s_mul_i32 s4, s46, s50
	v_readlane_b32 s15, v239, 0
	v_mfma_f32_16x16x32_bf16 v[104:107], v[170:173], v[202:205], 0
	s_add_u32 s18, s4, s15
	s_addc_u32 s19, s5, s36
	v_mfma_f32_16x16x32_bf16 v[92:95], v[162:165], v[210:213], 0
	s_cmp_lt_u32 s18, 0x900
	s_cselect_b64 s[4:5], -1, 0
	v_mfma_f32_16x16x32_bf16 v[88:91], v[170:173], v[210:213], 0
	global_store_dwordx4 v[242:243], v[48:51], off nt
	s_ashr_i32 s14, s18, 31
	s_lshr_b32 s14, s14, 29
	v_mfma_f32_16x16x32_bf16 v[76:79], v[162:165], v[218:221], 0
	s_add_i32 s14, s18, s14
	s_ashr_i32 s15, s14, 3
	v_mfma_f32_16x16x32_bf16 v[72:75], v[170:173], v[218:221], 0
	s_and_b32 s14, s14, -8
	s_sub_i32 s14, s18, s14
	v_mfma_f32_16x16x32_bf16 v[124:127], v[166:169], v[198:201], v[124:127]
	global_store_dwordx4 v[244:245], v[40:43], off nt
	s_cmp_lt_i32 s14, 0
	s_cselect_b32 s16, s37, 0x120
	v_mfma_f32_16x16x32_bf16 v[120:123], v[174:177], v[198:201], v[120:123]
	s_mul_i32 s14, s14, s16
	s_add_i32 s14, s14, s15
	v_mfma_f32_16x16x32_bf16 v[108:111], v[166:169], v[206:209], v[108:111]
	s_mul_hi_i32 s15, s14, 0x38e38e39
	s_lshr_b32 s16, s15, 31
	v_mfma_f32_16x16x32_bf16 v[104:107], v[174:177], v[206:209], v[104:107]
	global_store_dwordx4 v[246:247], v[32:35], off nt
	s_ashr_i32 s15, s15, 5
	s_add_i32 s15, s15, s16
	v_mfma_f32_16x16x32_bf16 v[92:95], v[166:169], v[214:217], v[92:95]
	s_lshl_b32 s16, s15, 2
	s_sub_i32 s17, 64, s16
	v_mfma_f32_16x16x32_bf16 v[88:91], v[174:177], v[214:217], v[88:91]
	s_min_i32 s17, s17, 4
	s_mulk_i32 s15, 0x90
	v_mfma_f32_16x16x32_bf16 v[76:79], v[166:169], v[222:225], v[76:79]
	global_store_dwordx4 v[248:249], v[24:27], off nt
	s_sub_i32 s15, s14, s15
	s_lshr_b32 s14, s15, 2
	v_mfma_f32_16x16x32_bf16 v[72:75], v[174:177], v[222:225], v[72:75]
	s_and_b32 s15, s15, 3
	s_add_i32 s16, s16, s15
	v_mfma_f32_16x16x32_bf16 v[116:119], v[178:181], v[194:197], 0
	s_ashr_i32 s17, s16, 31
	s_lshl_b64 s[18:19], s[16:17], 19
	v_mfma_f32_16x16x32_bf16 v[112:115], v[186:189], v[194:197], 0
	global_store_dwordx4 v[250:251], v[16:19], off nt
	v_readlane_b32 s24, v239, 47
	v_readlane_b32 s25, v239, 48
	v_mfma_f32_16x16x32_bf16 v[100:103], v[178:181], v[202:205], 0
	s_add_u32 s18, s24, s18
	s_addc_u32 s19, s25, s19
	v_mfma_f32_16x16x32_bf16 v[96:99], v[186:189], v[202:205], 0
	s_sub_u32 s98, s20, 0x40080
	s_subb_u32 s99, s21, 0
	v_mfma_f32_16x16x32_bf16 v[84:87], v[178:181], v[210:213], 0
	global_store_dwordx4 v[252:253], v[8:11], off nt
	s_cmp_lg_u64 s[4:5], 0
	s_cselect_b32 s17, s19, s99
	v_mfma_f32_16x16x32_bf16 v[80:83], v[186:189], v[210:213], 0
	s_cselect_b32 s24, s18, s98
	s_ashr_i32 s15, s14, 31
	v_mfma_f32_16x16x32_bf16 v[68:71], v[178:181], v[218:221], 0
	s_lshl_b64 s[98:99], s[14:15], 19
	s_add_u32 s40, s64, s98
	v_mfma_f32_16x16x32_bf16 v[64:67], v[186:189], v[218:221], 0
	global_store_dwordx4 v[254:255], v[0:3], off nt
	s_addc_u32 s41, s65, s99
	s_sub_u32 s98, s26, 0x100
	v_mfma_f32_16x16x32_bf16 v[116:119], v[182:185], v[198:201], v[116:119]
	s_subb_u32 s99, s27, 0
	s_cmp_lg_u64 s[4:5], 0
	v_mfma_f32_16x16x32_bf16 v[112:115], v[190:193], v[198:201], v[112:115]
	s_cselect_b32 s15, s41, s99
	s_cselect_b32 s25, s40, s98
	v_mfma_f32_16x16x32_bf16 v[100:103], v[182:185], v[206:209], v[100:103]
	v_mfma_f32_16x16x32_bf16 v[96:99], v[190:193], v[206:209], v[96:99]
	v_mfma_f32_16x16x32_bf16 v[84:87], v[182:185], v[214:217], v[84:87]
	v_mfma_f32_16x16x32_bf16 v[80:83], v[190:193], v[214:217], v[80:83]
	v_mfma_f32_16x16x32_bf16 v[68:71], v[182:185], v[222:225], v[68:71]
	v_mfma_f32_16x16x32_bf16 v[64:67], v[190:193], v[222:225], v[64:67]
	s_barrier
; #define PG8_STAGE(bufoff, gbase, voff) do { _Pragma("unroll") for (int _i = 0; _i < 2; ++_i) \
;         __builtin_amdgcn_global_load_lds((const unsigned*)((const char*)(gbase) + (voff)[_i]), (PG8_LAS unsigned*)(lds + (bufoff) + ldsw + _i * 8192), 16, 0, PG8_LOAD_AUX); } while (0)
; #define PG8_LDA(dst, b, h) do { _Pragma("unroll") for (int m = 0; m < 4; ++m) _Pragma("unroll") for (int k = 0; k < 2; ++k) dst[m][k] = *(const PG8_LAS bf16x8*)(lds + PG8_SA(b, h) + aoff + m * 2048 + k * 1024); } while (0)
; #define PG8_MMA(ai, bj, At, Bt) do { __builtin_amdgcn_s_setprio(1); _Pragma("unroll") for (int m = 0; m < 4; ++m) _Pragma("unroll") for (int n = 0; n < 2; ++n) _Pragma("unroll") for (int k = 0; k < 2; ++k) \
;         acc[ai][bj][m][n] = __builtin_amdgcn_mfma_f32_16x16x32_bf16(Bt[n][k], At[m][k], acc[ai][bj][m][n], 0, 0, 0); __builtin_amdgcn_s_setprio(0); } while (0)
; #define PG8_WAIT_V(n) asm volatile("s_waitcnt vmcnt(" #n ")" ::: "memory")
; #define PG8_WAIT_L(n) asm volatile("s_waitcnt lgkmcnt(" #n ")" ::: "memory")
; #define PG8_BAR __builtin_amdgcn_s_barrier()
; #define PG8_SCHED __builtin_amdgcn_sched_barrier(0)
; template <class Epi, class Sched, bool ALIGN_EPI = false, bool SP2 = false>
; __device__ __forceinline__ void gemm_phase(PG8_LAS unsigned char* lds, const Gemm g, const Sched& S, const Epi& E) {
;     ...
;             PG8_LDA(At, 0, 1); PG8_STAGE(PG8_SB(0, 0), b2, voffB); PG8_STAGE(PG8_SB(0, 1), b2 + hstepB, voffB); PG8_STAGE(PG8_SA(0, 0), a2, voffA);
;             PG8_WAIT_V(8); PG8_WAIT_L(0); PG8_BAR; PG8_MMA(1, 0, At, B0); PG8_MMA(1, 1, At, B1); PG8_BAR; PG8_SCHED;
	s_add_i32 s29, s51, s33
	v_lshl_add_u64 v[226:227], s[22:23], 0, v[130:131]
	s_mov_b32 m0, s29
	ds_read_b128 v[194:197], v160 offset:16384
	ds_read_b128 v[198:201], v160 offset:17408
	ds_read_b128 v[202:205], v160 offset:18432
	ds_read_b128 v[206:209], v160 offset:19456
	ds_read_b128 v[210:213], v160 offset:20480
	ds_read_b128 v[214:217], v160 offset:21504
	ds_read_b128 v[218:221], v160 offset:22528
	ds_read_b128 v[222:225], v160 offset:23552
	global_load_lds_dwordx4 v[226:227], off
	s_add_i32 m0, s29, 0x2000
	s_add_u32 s30, s22, 0x10000
	v_lshl_add_u64 v[228:229], s[22:23], 0, v[134:135]
	s_addc_u32 s31, s23, 0
	s_add_i32 s29, s52, s33
	global_load_lds_dwordx4 v[228:229], off
	v_lshl_add_u64 v[230:231], s[30:31], 0, v[130:131]
	s_mov_b32 m0, s29
	v_lshl_add_u64 v[232:233], s[34:35], 0, v[132:133]
	global_load_lds_dwordx4 v[230:231], off
	v_lshl_add_u64 v[230:231], s[30:31], 0, v[134:135]
	s_add_i32 m0, s29, 0x2000
	s_nop 0
	global_load_lds_dwordx4 v[230:231], off
	v_lshl_add_u64 v[230:231], s[34:35], 0, v[128:129]
	s_mov_b32 m0, s42
	s_nop 0
	global_load_lds_dwordx4 v[230:231], off
	s_mov_b32 m0, s43
	s_nop 0
	global_load_lds_dwordx4 v[232:233], off
	s_waitcnt vmcnt(16)
	s_waitcnt lgkmcnt(0)
	s_barrier
	s_waitcnt lgkmcnt(0)
	v_mfma_f32_16x16x32_bf16 v[60:63], v[162:165], v[194:197], 0
	v_mfma_f32_16x16x32_bf16 v[56:59], v[170:173], v[194:197], 0
	v_mfma_f32_16x16x32_bf16 v[44:47], v[162:165], v[202:205], 0
	v_mfma_f32_16x16x32_bf16 v[40:43], v[170:173], v[202:205], 0
	v_mfma_f32_16x16x32_bf16 v[28:31], v[162:165], v[210:213], 0
	v_mfma_f32_16x16x32_bf16 v[24:27], v[170:173], v[210:213], 0
	v_mfma_f32_16x16x32_bf16 v[12:15], v[162:165], v[218:221], 0
	v_mfma_f32_16x16x32_bf16 v[8:11], v[170:173], v[218:221], 0
	v_mfma_f32_16x16x32_bf16 v[60:63], v[166:169], v[198:201], v[60:63]
	v_mfma_f32_16x16x32_bf16 v[56:59], v[174:177], v[198:201], v[56:59]
	v_mfma_f32_16x16x32_bf16 v[44:47], v[166:169], v[206:209], v[44:47]
	v_mfma_f32_16x16x32_bf16 v[40:43], v[174:177], v[206:209], v[40:43]
	v_mfma_f32_16x16x32_bf16 v[28:31], v[166:169], v[214:217], v[28:31]
	v_mfma_f32_16x16x32_bf16 v[24:27], v[174:177], v[214:217], v[24:27]
	v_mfma_f32_16x16x32_bf16 v[12:15], v[166:169], v[222:225], v[12:15]
	v_mfma_f32_16x16x32_bf16 v[8:11], v[174:177], v[222:225], v[8:11]
	v_mfma_f32_16x16x32_bf16 v[52:55], v[178:181], v[194:197], 0
	v_mfma_f32_16x16x32_bf16 v[48:51], v[186:189], v[194:197], 0
	v_mfma_f32_16x16x32_bf16 v[36:39], v[178:181], v[202:205], 0
	v_mfma_f32_16x16x32_bf16 v[32:35], v[186:189], v[202:205], 0
	v_mfma_f32_16x16x32_bf16 v[20:23], v[178:181], v[210:213], 0
	v_mfma_f32_16x16x32_bf16 v[16:19], v[186:189], v[210:213], 0
	v_mfma_f32_16x16x32_bf16 v[4:7], v[178:181], v[218:221], 0
	v_mfma_f32_16x16x32_bf16 v[0:3], v[186:189], v[218:221], 0
	v_mfma_f32_16x16x32_bf16 v[52:55], v[182:185], v[198:201], v[52:55]
	v_mfma_f32_16x16x32_bf16 v[48:51], v[190:193], v[198:201], v[48:51]
	v_mfma_f32_16x16x32_bf16 v[36:39], v[182:185], v[206:209], v[36:39]
	v_mfma_f32_16x16x32_bf16 v[32:35], v[190:193], v[206:209], v[32:35]
	v_mfma_f32_16x16x32_bf16 v[20:23], v[182:185], v[214:217], v[20:23]
	v_mfma_f32_16x16x32_bf16 v[16:19], v[190:193], v[214:217], v[16:19]
	v_mfma_f32_16x16x32_bf16 v[4:7], v[182:185], v[222:225], v[4:7]
	v_mfma_f32_16x16x32_bf16 v[0:3], v[190:193], v[222:225], v[0:3]
	s_barrier
	s_branch .Lkmid_P1

; __device__ __forceinline__ unsigned cvt_pk_bf16(float lo, float hi) { const cvt_f32x2_t v = {lo, hi}; const cvt_bf16x2_t b = __builtin_convertvector(v, cvt_bf16x2_t); return __builtin_bit_cast(unsigned, b); }
; __device__ __forceinline__ unsigned swap8(unsigned v) { return (unsigned)__builtin_amdgcn_update_dpp(0, (int)v, 0x128  , 0xF, 0xF, false); }
; __device__ __forceinline__ void wide_store(bf16_t* O, int ldc, int rowg  , int col0  , int fr, u32x4 w0, u32x4 w1) {
;     const bool lo = fr < 8;
;     u32x4 snd = lo ? w1 : w0, rcv;
;     rcv.x = swap8(snd.x); rcv.y = swap8(snd.y); rcv.z = swap8(snd.z); rcv.w = swap8(snd.w);
;     const u32x4 first = lo ? w0 : rcv, second = lo ? rcv : w1;
;     bf16_t* p = O + (size_t)(rowg + (fr & 7)) * ldc + col0 + (lo ? 0 : 32);
;     __builtin_nontemporal_store(first, (u32x4*)p); __builtin_nontemporal_store(second, (u32x4*)(p + (size_t)8 * ldc));
; }
;     __device__ __forceinline__ void operator()(const f32x4 (&acc)[2][2][4][2], const Unit& u, int wr, int wc, int fr, int fq) const {
;         const int col0 = u.pn * BM + wc * 64 + 8 * fq;
; #pragma unroll
;         for (int ai = 0; ai < 2; ++ai)
; #pragma unroll
;             for (int m = 0; m < 4; ++m) { const int rowg = u.pm * BM + ai * HALF + wr * 64 + m * 16;
;                 const float sc = slots ? rstd_from_slots(slots, rowg + fr, fq) : 1.0f;
;                 u32x4 w[2];
; #pragma unroll
;                 for (int bj = 0; bj < 2; ++bj) { const f32x4 v0 = acc[ai][bj][m][0] * sc, v1 = acc[ai][bj][m][1] * sc;
;                     w[bj].x = cvt_pk_bf16(v0[0], v0[1]); w[bj].y = cvt_pk_bf16(v0[2], v0[3]); w[bj].z = cvt_pk_bf16(v1[0], v1[1]); w[bj].w = cvt_pk_bf16(v1[2], v1[3]); }
;                 wide_store(O, ldc, rowg, col0, fr, w[0], w[1]); }
.LBB0_218:
	v_readlane_b32 s30, v239, 49
	v_readlane_b32 s31, v239, 50
	s_lshl_b32 s0, s0, 8
	v_lshl_or_b32 v162, s1, 8, v147
	v_add_u32_e32 v164, s0, v148
	v_ashrrev_i32_e32 v163, 31, v162
	s_mov_b32 s98, 0x24000
	s_mov_b32 s99, 0
	v_lshlrev_b64 v[162:163], 1, v[162:163]
	v_mov_b64_e32 v[168:169], s[30:31]
	v_mad_i64_i32 v[164:165], s[20:21], v164, s53, v[168:169]
	v_lshl_add_u64 v[162:163], v[162:163], 0, v[136:137]
	v_lshl_add_u64 v[164:165], v[164:165], 0, v[162:163]
	v_cvt_pk_bf16_f32 v124, v124, v125
	v_cvt_pk_bf16_f32 v125, v126, v127
	v_cvt_pk_bf16_f32 v126, v120, v121
	v_cvt_pk_bf16_f32 v127, v122, v123
	v_cvt_pk_bf16_f32 v116, v116, v117
	v_cvt_pk_bf16_f32 v117, v118, v119
	v_cvt_pk_bf16_f32 v118, v112, v113
	v_cvt_pk_bf16_f32 v119, v114, v115
	v_cvt_pk_bf16_f32 v108, v108, v109
	v_cvt_pk_bf16_f32 v109, v110, v111
	v_cvt_pk_bf16_f32 v110, v104, v105
	v_cvt_pk_bf16_f32 v111, v106, v107
	v_cvt_pk_bf16_f32 v100, v100, v101
	v_cvt_pk_bf16_f32 v101, v102, v103
	v_cvt_pk_bf16_f32 v102, v96, v97
	v_cvt_pk_bf16_f32 v103, v98, v99
	s_not_b64 vcc, s[2:3]
	v_cndmask_b32_dpp v112, v124, v116, vcc row_ror:8 row_mask:0xf bank_mask:0xf
	v_cndmask_b32_dpp v113, v125, v117, vcc row_ror:8 row_mask:0xf bank_mask:0xf
	v_cndmask_b32_dpp v114, v126, v118, vcc row_ror:8 row_mask:0xf bank_mask:0xf
	v_cndmask_b32_dpp v115, v127, v119, vcc row_ror:8 row_mask:0xf bank_mask:0xf
	v_cndmask_b32_dpp v96, v108, v100, vcc row_ror:8 row_mask:0xf bank_mask:0xf
	v_cndmask_b32_dpp v97, v109, v101, vcc row_ror:8 row_mask:0xf bank_mask:0xf
	v_cndmask_b32_dpp v98, v110, v102, vcc row_ror:8 row_mask:0xf bank_mask:0xf
	v_cndmask_b32_dpp v99, v111, v103, vcc row_ror:8 row_mask:0xf bank_mask:0xf
	s_mov_b64 vcc, s[2:3]
	v_cndmask_b32_dpp v120, v116, v124, vcc row_ror:8 row_mask:0xf bank_mask:0xf
	v_cndmask_b32_dpp v121, v117, v125, vcc row_ror:8 row_mask:0xf bank_mask:0xf
	v_cndmask_b32_dpp v122, v118, v126, vcc row_ror:8 row_mask:0xf bank_mask:0xf
	v_cndmask_b32_dpp v123, v119, v127, vcc row_ror:8 row_mask:0xf bank_mask:0xf
	v_cndmask_b32_dpp v104, v100, v108, vcc row_ror:8 row_mask:0xf bank_mask:0xf
	v_cndmask_b32_dpp v105, v101, v109, vcc row_ror:8 row_mask:0xf bank_mask:0xf
	v_cndmask_b32_dpp v106, v102, v110, vcc row_ror:8 row_mask:0xf bank_mask:0xf
	v_cndmask_b32_dpp v107, v103, v111, vcc row_ror:8 row_mask:0xf bank_mask:0xf
	global_store_dwordx4 v[164:165], v[120:123], off nt
	v_lshl_add_u64 v[166:167], v[164:165], 0, s[98:99]
	global_store_dwordx4 v[166:167], v[112:115], off nt
	v_lshl_add_u64 v[164:165], v[166:167], 0, s[98:99]
	global_store_dwordx4 v[164:165], v[104:107], off nt
	v_lshl_add_u64 v[166:167], v[164:165], 0, s[98:99]
	global_store_dwordx4 v[166:167], v[96:99], off nt
	v_cvt_pk_bf16_f32 v92, v92, v93
	v_cvt_pk_bf16_f32 v93, v94, v95
	v_cvt_pk_bf16_f32 v94, v88, v89
	v_cvt_pk_bf16_f32 v95, v90, v91
	v_cvt_pk_bf16_f32 v84, v84, v85
	v_cvt_pk_bf16_f32 v85, v86, v87
	v_cvt_pk_bf16_f32 v86, v80, v81
	v_cvt_pk_bf16_f32 v87, v82, v83
	v_cvt_pk_bf16_f32 v76, v76, v77
	v_cvt_pk_bf16_f32 v77, v78, v79
	v_cvt_pk_bf16_f32 v78, v72, v73
	v_cvt_pk_bf16_f32 v79, v74, v75
	v_cvt_pk_bf16_f32 v68, v68, v69
	v_cvt_pk_bf16_f32 v69, v70, v71
	v_cvt_pk_bf16_f32 v70, v64, v65
	v_cvt_pk_bf16_f32 v71, v66, v67
	s_not_b64 vcc, s[2:3]
	v_cndmask_b32_dpp v80, v92, v84, vcc row_ror:8 row_mask:0xf bank_mask:0xf
	v_cndmask_b32_dpp v81, v93, v85, vcc row_ror:8 row_mask:0xf bank_mask:0xf
	v_cndmask_b32_dpp v82, v94, v86, vcc row_ror:8 row_mask:0xf bank_mask:0xf
	v_cndmask_b32_dpp v83, v95, v87, vcc row_ror:8 row_mask:0xf bank_mask:0xf
	v_cndmask_b32_dpp v64, v76, v68, vcc row_ror:8 row_mask:0xf bank_mask:0xf
	v_cndmask_b32_dpp v65, v77, v69, vcc row_ror:8 row_mask:0xf bank_mask:0xf
	v_cndmask_b32_dpp v66, v78, v70, vcc row_ror:8 row_mask:0xf bank_mask:0xf
	v_cndmask_b32_dpp v67, v79, v71, vcc row_ror:8 row_mask:0xf bank_mask:0xf
	s_mov_b64 vcc, s[2:3]
	v_cndmask_b32_dpp v88, v84, v92, vcc row_ror:8 row_mask:0xf bank_mask:0xf
	v_cndmask_b32_dpp v89, v85, v93, vcc row_ror:8 row_mask:0xf bank_mask:0xf
	v_cndmask_b32_dpp v90, v86, v94, vcc row_ror:8 row_mask:0xf bank_mask:0xf
	v_cndmask_b32_dpp v91, v87, v95, vcc row_ror:8 row_mask:0xf bank_mask:0xf
	v_cndmask_b32_dpp v72, v68, v76, vcc row_ror:8 row_mask:0xf bank_mask:0xf
	v_cndmask_b32_dpp v73, v69, v77, vcc row_ror:8 row_mask:0xf bank_mask:0xf
	v_cndmask_b32_dpp v74, v70, v78, vcc row_ror:8 row_mask:0xf bank_mask:0xf
	v_cndmask_b32_dpp v75, v71, v79, vcc row_ror:8 row_mask:0xf bank_mask:0xf
	v_lshl_add_u64 v[164:165], v[166:167], 0, s[98:99]
	global_store_dwordx4 v[164:165], v[88:91], off nt
	v_lshl_add_u64 v[166:167], v[164:165], 0, s[98:99]
	global_store_dwordx4 v[166:167], v[80:83], off nt
	v_lshl_add_u64 v[164:165], v[166:167], 0, s[98:99]
; __device__ __forceinline__ unsigned cvt_pk_bf16(float lo, float hi) { const cvt_f32x2_t v = {lo, hi}; const cvt_bf16x2_t b = __builtin_convertvector(v, cvt_bf16x2_t); return __builtin_bit_cast(unsigned, b); }
; __device__ __forceinline__ unsigned swap8(unsigned v) { return (unsigned)__builtin_amdgcn_update_dpp(0, (int)v, 0x128  , 0xF, 0xF, false); }
; __device__ __forceinline__ void wide_store(bf16_t* O, int ldc, int rowg  , int col0  , int fr, u32x4 w0, u32x4 w1) {
;     const bool lo = fr < 8;
;     u32x4 snd = lo ? w1 : w0, rcv;
;     rcv.x = swap8(snd.x); rcv.y = swap8(snd.y); rcv.z = swap8(snd.z); rcv.w = swap8(snd.w);
;     const u32x4 first = lo ? w0 : rcv, second = lo ? rcv : w1;
;     bf16_t* p = O + (size_t)(rowg + (fr & 7)) * ldc + col0 + (lo ? 0 : 32);
;     __builtin_nontemporal_store(first, (u32x4*)p); __builtin_nontemporal_store(second, (u32x4*)(p + (size_t)8 * ldc));
; }
;     __device__ __forceinline__ void operator()(const f32x4 (&acc)[2][2][4][2], const Unit& u, int wr, int wc, int fr, int fq) const {
;     ...
;             for (int m = 0; m < 4; ++m) { const int rowg = u.pm * BM + ai * HALF + wr * 64 + m * 16;
;                 const float sc = slots ? rstd_from_slots(slots, rowg + fr, fq) : 1.0f;
;                 u32x4 w[2];
; #pragma unroll
;                 for (int bj = 0; bj < 2; ++bj) { const f32x4 v0 = acc[ai][bj][m][0] * sc, v1 = acc[ai][bj][m][1] * sc;
;                     w[bj].x = cvt_pk_bf16(v0[0], v0[1]); w[bj].y = cvt_pk_bf16(v0[2], v0[3]); w[bj].z = cvt_pk_bf16(v1[0], v1[1]); w[bj].w = cvt_pk_bf16(v1[2], v1[3]); }
;                 wide_store(O, ldc, rowg, col0, fr, w[0], w[1]); }
	global_store_dwordx4 v[164:165], v[72:75], off nt
	v_lshl_add_u64 v[166:167], v[164:165], 0, s[98:99]
	global_store_dwordx4 v[166:167], v[64:67], off nt
	v_cvt_pk_bf16_f32 v60, v60, v61
	v_cvt_pk_bf16_f32 v61, v62, v63
	v_cvt_pk_bf16_f32 v62, v56, v57
	v_cvt_pk_bf16_f32 v63, v58, v59
	v_cvt_pk_bf16_f32 v52, v52, v53
	v_cvt_pk_bf16_f32 v53, v54, v55
	v_cvt_pk_bf16_f32 v54, v48, v49
	v_cvt_pk_bf16_f32 v55, v50, v51
	v_cvt_pk_bf16_f32 v44, v44, v45
	v_cvt_pk_bf16_f32 v45, v46, v47
	v_cvt_pk_bf16_f32 v46, v40, v41
	v_cvt_pk_bf16_f32 v47, v42, v43
	v_cvt_pk_bf16_f32 v36, v36, v37
	v_cvt_pk_bf16_f32 v37, v38, v39
	v_cvt_pk_bf16_f32 v38, v32, v33
	v_cvt_pk_bf16_f32 v39, v34, v35
	s_not_b64 vcc, s[2:3]
	v_cndmask_b32_dpp v48, v60, v52, vcc row_ror:8 row_mask:0xf bank_mask:0xf
	v_cndmask_b32_dpp v49, v61, v53, vcc row_ror:8 row_mask:0xf bank_mask:0xf
	v_cndmask_b32_dpp v50, v62, v54, vcc row_ror:8 row_mask:0xf bank_mask:0xf
	v_cndmask_b32_dpp v51, v63, v55, vcc row_ror:8 row_mask:0xf bank_mask:0xf
	v_cndmask_b32_dpp v32, v44, v36, vcc row_ror:8 row_mask:0xf bank_mask:0xf
	v_cndmask_b32_dpp v33, v45, v37, vcc row_ror:8 row_mask:0xf bank_mask:0xf
	v_cndmask_b32_dpp v34, v46, v38, vcc row_ror:8 row_mask:0xf bank_mask:0xf
	v_cndmask_b32_dpp v35, v47, v39, vcc row_ror:8 row_mask:0xf bank_mask:0xf
	s_mov_b64 vcc, s[2:3]
	v_cndmask_b32_dpp v56, v52, v60, vcc row_ror:8 row_mask:0xf bank_mask:0xf
	v_cndmask_b32_dpp v57, v53, v61, vcc row_ror:8 row_mask:0xf bank_mask:0xf
	v_cndmask_b32_dpp v58, v54, v62, vcc row_ror:8 row_mask:0xf bank_mask:0xf
	v_cndmask_b32_dpp v59, v55, v63, vcc row_ror:8 row_mask:0xf bank_mask:0xf
	v_cndmask_b32_dpp v40, v36, v44, vcc row_ror:8 row_mask:0xf bank_mask:0xf
	v_cndmask_b32_dpp v41, v37, v45, vcc row_ror:8 row_mask:0xf bank_mask:0xf
	v_cndmask_b32_dpp v42, v38, v46, vcc row_ror:8 row_mask:0xf bank_mask:0xf
	v_cndmask_b32_dpp v43, v39, v47, vcc row_ror:8 row_mask:0xf bank_mask:0xf
	s_mov_b32 s98, 0x144000
	v_lshl_add_u64 v[240:241], v[166:167], 0, s[98:99]
	s_mov_b32 s98, 0x24000
	v_lshl_add_u64 v[242:243], v[240:241], 0, s[98:99]
	v_lshl_add_u64 v[244:245], v[242:243], 0, s[98:99]
	v_lshl_add_u64 v[246:247], v[244:245], 0, s[98:99]
	v_cvt_pk_bf16_f32 v28, v28, v29
	v_cvt_pk_bf16_f32 v29, v30, v31
	v_cvt_pk_bf16_f32 v30, v24, v25
	v_cvt_pk_bf16_f32 v31, v26, v27
	v_cvt_pk_bf16_f32 v20, v20, v21
	v_cvt_pk_bf16_f32 v21, v22, v23
	v_cvt_pk_bf16_f32 v22, v16, v17
	v_cvt_pk_bf16_f32 v23, v18, v19
	v_cvt_pk_bf16_f32 v12, v12, v13
	v_cvt_pk_bf16_f32 v13, v14, v15
	v_cvt_pk_bf16_f32 v14, v8, v9
	v_cvt_pk_bf16_f32 v15, v10, v11
	v_cvt_pk_bf16_f32 v4, v4, v5
	v_cvt_pk_bf16_f32 v5, v6, v7
	v_cvt_pk_bf16_f32 v6, v0, v1
	v_cvt_pk_bf16_f32 v7, v2, v3
	s_not_b64 vcc, s[2:3]
	v_cndmask_b32_dpp v16, v28, v20, vcc row_ror:8 row_mask:0xf bank_mask:0xf
	v_cndmask_b32_dpp v17, v29, v21, vcc row_ror:8 row_mask:0xf bank_mask:0xf
	v_cndmask_b32_dpp v18, v30, v22, vcc row_ror:8 row_mask:0xf bank_mask:0xf
	v_cndmask_b32_dpp v19, v31, v23, vcc row_ror:8 row_mask:0xf bank_mask:0xf
	v_cndmask_b32_dpp v0, v12, v4, vcc row_ror:8 row_mask:0xf bank_mask:0xf
	v_cndmask_b32_dpp v1, v13, v5, vcc row_ror:8 row_mask:0xf bank_mask:0xf
	v_cndmask_b32_dpp v2, v14, v6, vcc row_ror:8 row_mask:0xf bank_mask:0xf
	v_cndmask_b32_dpp v3, v15, v7, vcc row_ror:8 row_mask:0xf bank_mask:0xf
	s_mov_b64 vcc, s[2:3]
	v_cndmask_b32_dpp v24, v20, v28, vcc row_ror:8 row_mask:0xf bank_mask:0xf
	v_cndmask_b32_dpp v25, v21, v29, vcc row_ror:8 row_mask:0xf bank_mask:0xf
	v_cndmask_b32_dpp v26, v22, v30, vcc row_ror:8 row_mask:0xf bank_mask:0xf
	v_cndmask_b32_dpp v27, v23, v31, vcc row_ror:8 row_mask:0xf bank_mask:0xf
	v_cndmask_b32_dpp v8, v4, v12, vcc row_ror:8 row_mask:0xf bank_mask:0xf
	v_cndmask_b32_dpp v9, v5, v13, vcc row_ror:8 row_mask:0xf bank_mask:0xf
	v_cndmask_b32_dpp v10, v6, v14, vcc row_ror:8 row_mask:0xf bank_mask:0xf
	v_cndmask_b32_dpp v11, v7, v15, vcc row_ror:8 row_mask:0xf bank_mask:0xf
	v_lshl_add_u64 v[248:249], v[246:247], 0, s[98:99]
	v_lshl_add_u64 v[250:251], v[248:249], 0, s[98:99]
	v_lshl_add_u64 v[252:253], v[250:251], 0, s[98:99]
	v_lshl_add_u64 v[254:255], v[252:253], 0, s[98:99]
	s_andn2_b64 vcc, exec, s[4:5]
	s_mov_b64 s[0:1], -1
	s_cbranch_vccz .Lqkv_defer_218
	global_store_dwordx4 v[240:241], v[56:59], off nt
	global_store_dwordx4 v[242:243], v[48:51], off nt
	global_store_dwordx4 v[244:245], v[40:43], off nt
	global_store_dwordx4 v[246:247], v[32:35], off nt
	global_store_dwordx4 v[248:249], v[24:27], off nt
	global_store_dwordx4 v[250:251], v[16:19], off nt
	global_store_dwordx4 v[252:253], v[8:11], off nt
	global_store_dwordx4 v[254:255], v[0:3], off nt
.Lqkv_defer_218:
	s_cbranch_vccnz .LBB0_211
	s_andn2_b64 vcc, exec, s[8:9]
	s_cbranch_vccnz .LBB0_210
	s_barrier
	s_branch .LBB0_210

; #define PG8_STAGE(bufoff, gbase, voff) do { _Pragma("unroll") for (int _i = 0; _i < 2; ++_i) \
;         __builtin_amdgcn_global_load_lds((const unsigned*)((const char*)(gbase) + (voff)[_i]), (PG8_LAS unsigned*)(lds + (bufoff) + ldsw + _i * 8192), 16, 0, PG8_LOAD_AUX); } while (0)
; #define PG8_LDA(dst, b, h) do { _Pragma("unroll") for (int m = 0; m < 4; ++m) _Pragma("unroll") for (int k = 0; k < 2; ++k) dst[m][k] = *(const PG8_LAS bf16x8*)(lds + PG8_SA(b, h) + aoff + m * 2048 + k * 1024); } while (0)
; #define PG8_WAIT_V(n) asm volatile("s_waitcnt vmcnt(" #n ")" ::: "memory")
; template <class Epi, class Sched, bool ALIGN_EPI = false, bool SP2 = false>
; __device__ __forceinline__ void gemm_phase(PG8_LAS unsigned char* lds, const Gemm g, const Sched& S, const Epi& E) {
;     ...
;         PG8_STAGE(PG8_SB(1, 0), cB + kstep, voffB); PG8_STAGE(PG8_SA(1, 0), cA + kstep, voffA); PG8_STAGE(PG8_SB(1, 1), cB + hstepB + kstep, voffB);
;         PG8_WAIT_V(6); PG8_BAR;
;     } else {
;         PG8_STAGE(PG8_SB(0, 0), cB, voffB); PG8_STAGE(PG8_SA(0, 0), cA, voffA); PG8_STAGE(PG8_SB(0, 1), cB + hstepB, voffB); PG8_STAGE(PG8_SA(0, 1), cA + hstepA, voffA);
;         if (wr == 1) PG8_BAR;
;         PG8_WAIT_V(4); PG8_BAR;
;         PG8_STAGE(PG8_SB(1, 0), cB + kstep, voffB); PG8_STAGE(PG8_SA(1, 0), cA + kstep, voffA); PG8_STAGE(PG8_SB(1, 1), cB + hstepB + kstep, voffB);
;         PG8_WAIT_V(6); PG8_BAR;
;     }
;     for (;;) {
;         const bool has_next = S.next(ui + 1, nxt);
;         const char* nA = has_next ? (const char*)g.A + (size_t)nxt.pm * tstepA + (size_t)nxt.pn * apn : cA; const char* nB = has_next ? (const char*)g.Bt + (size_t)nxt.pn * tstepB : cB;
;         for (int t = 0; t < nt; t += 2) {
;             const bool last = (t == nt - 2);
;             const char* a1 = cA + (size_t)(t + 1) * kstep;
;             const char* a2 = last ? nA : cA + (size_t)(t + 2) * kstep; const char* b2 = last ? nB : cB + (size_t)(t + 2) * kstep;
;             const char* a3 = a2 + kstep; const char* b3 = b2 + kstep;
;             if (last && has_next) S.a_ready(nxt);
;             if constexpr (SP2) {
;             PG8_LDB(B0, 0, 0); PG8_LDB(B1, 0, 1); PG8_SCHED; PG8_LDA(At, 0, 0); PG8_STAGE(PG8_SA(1, 1), a1 + hstepA, voffA);
;             PG8_WAIT_V(8); PG8_WAIT_L(0); PG8_BAR; PG8_MMA(0, 0, At, B0); PG8_MMA(0, 1, At, B1); PG8_BAR; PG8_SCHED;
.LBB0_363:
	s_mov_b64 s[10:11], 0x80
	s_and_b32 s14, s5, 3
	s_add_i32 m0, s44, 0x18000
	v_lshl_add_u64 v[6:7], v[6:7], 0, s[10:11]
	s_lshl_b32 s15, s4, 6
	s_lshl_b32 s1, s4, 13
	s_lshl_b32 s12, s14, 12
	global_load_lds_dwordx4 v[6:7], off
	v_lshl_add_u64 v[4:5], v[4:5], 0, s[10:11]
	s_add_i32 m0, s44, 0x1a000
	s_add_i32 s49, s44, 0x8000
	s_add_i32 s50, s44, 0xa000
	global_load_lds_dwordx4 v[4:5], off
	v_lshl_add_u64 v[0:1], v[0:1], 0, s[10:11]
	s_mov_b32 m0, s49
	s_add_u32 s4, s22, 0x10080
	global_load_lds_dwordx4 v[0:1], off
	v_lshl_add_u64 v[0:1], v[2:3], 0, s[10:11]
	s_mov_b32 m0, s50
	s_addc_u32 s5, s23, 0
	global_load_lds_dwordx4 v[0:1], off
	s_add_i32 m0, s44, 0x1c000
	v_lshl_add_u64 v[0:1], s[4:5], 0, v[132:133]
	global_load_lds_dwordx4 v[0:1], off
	v_lshl_add_u64 v[0:1], s[4:5], 0, v[128:129]
	s_add_i32 m0, s44, 0x1e000
	v_lshlrev_b32_e32 v4, 2, v154
	global_load_lds_dwordx4 v[0:1], off
	s_waitcnt vmcnt(8)
	s_barrier
	v_bfe_u32 v1, v154, 4, 2
	v_and_b32_e32 v0, 15, v154
	v_lshlrev_b32_e32 v2, 3, v1
	v_lshlrev_b32_e32 v1, 4, v1
	v_lshl_or_b32 v3, v0, 6, v1
	v_and_b32_e32 v4, 32, v4
	v_bitop3_b32 v3, v3, s1, v4 bitop3:0xde
	v_lshlrev_b32_e32 v5, 6, v154
	s_movk_i32 s1, 0x3c0
	v_and_or_b32 v1, v5, s1, v1
	s_cmpk_lt_u32 s3, 0x100
	v_bitop3_b32 v146, s12, v1, v4 bitop3:0xf6
	s_cselect_b64 s[12:13], -1, 0
	v_lshl_or_b32 v147, s14, 6, v2
	v_and_b32_e32 v1, 7, v154
	s_add_i32 s4, s15, 0x80
	s_add_i32 s5, s15, 0x90
	s_add_i32 s14, s15, 0xa0
	s_add_i32 s16, s15, 0xb0
	v_or_b32_e32 v148, s15, v1
	v_or_b32_e32 v152, s4, v1
	v_or_b32_e32 v156, s5, v1
	v_or_b32_e32 v157, s14, v1
	v_or_b32_e32 v158, s16, v1
	v_lshlrev_b32_e32 v1, 8, v154
	v_and_b32_e32 v1, 0x38000, v1
	v_lshlrev_b32_e32 v2, 11, v11
	v_or3_b32 v1, v9, v1, v2
	v_add_u32_e32 v138, v1, v10
	v_lshlrev_b32_e32 v1, 4, v8
	s_sext_i32_i16 s1, s2
	s_waitcnt vmcnt(6)
	v_cmp_gt_u32_e64 s[2:3], 8, v0
	v_and_b32_e32 v1, 0x78000, v1
	v_or3_b32 v1, v9, v1, v2
	v_cndmask_b32_e64 v0, 32, 0, s[2:3]
	s_add_i32 s53, 0, 0x10000
	s_add_i32 s54, 0, 0x14000
	s_ashr_i32 s51, s86, 31
	s_mov_b32 s52, s86
	v_or_b32_e32 v149, 16, v148
	v_or_b32_e32 v150, 32, v148
	v_or_b32_e32 v151, 48, v148
	v_mov_b32_e32 v139, v137
	v_add_u32_e32 v140, v1, v10
	v_mov_b32_e32 v141, v137
	v_mov_b64_e32 v[142:143], 0x900
	v_mov_b64_e32 v[144:145], 0x8ff
	v_add_u32_e32 v159, s53, v146
	v_add_u32_e32 v160, s54, v146
	v_add_u32_e32 v161, 0, v3
	s_movk_i32 s55, 0x4800
	v_lshlrev_b32_e32 v136, 1, v0
	s_mov_b32 s56, 0x24000
	s_barrier
	s_add_u32 s20, s20, 0x40080
	s_addc_u32 s21, s21, 0
	s_add_u32 s26, s22, 0x100
	s_addc_u32 s27, s23, 0
	s_mov_b32 s28, -2
	ds_read_b128 v[162:165], v159
	ds_read_b128 v[166:169], v159 offset:1024
	ds_read_b128 v[170:173], v159 offset:2048
	ds_read_b128 v[174:177], v159 offset:3072
	ds_read_b128 v[178:181], v160
	ds_read_b128 v[182:185], v160 offset:1024
	ds_read_b128 v[186:189], v160 offset:2048
	ds_read_b128 v[190:193], v160 offset:3072
	s_add_u32 s22, s20, 0xfffc0080
	s_addc_u32 s23, s21, -1
	s_cmp_eq_u32 s28, 12
	s_cselect_b32 s35, s17, s23
	s_cselect_b32 s34, s24, s22
	s_cselect_b32 s23, s15, s27
	s_cselect_b32 s22, s25, s26
	v_lshl_add_u64 v[226:227], s[20:21], 0, v[138:139]
	s_add_i32 m0, s44, 0xc000
	ds_read_b128 v[194:197], v161
	ds_read_b128 v[198:201], v161 offset:1024
	ds_read_b128 v[202:205], v161 offset:2048
	ds_read_b128 v[206:209], v161 offset:3072
	ds_read_b128 v[210:213], v161 offset:4096
	ds_read_b128 v[214:217], v161 offset:5120
	ds_read_b128 v[218:221], v161 offset:6144
	ds_read_b128 v[222:225], v161 offset:7168
	global_load_lds_dwordx4 v[226:227], off
	v_lshl_add_u64 v[226:227], s[20:21], 0, v[140:141]
	s_add_i32 m0, s44, 0xe000
	s_nop 0
	global_load_lds_dwordx4 v[226:227], off
	s_waitcnt vmcnt(8)
	s_waitcnt lgkmcnt(0)
	s_barrier
; #define PG8_STAGE(bufoff, gbase, voff) do { _Pragma("unroll") for (int _i = 0; _i < 2; ++_i) \
;         __builtin_amdgcn_global_load_lds((const unsigned*)((const char*)(gbase) + (voff)[_i]), (PG8_LAS unsigned*)(lds + (bufoff) + ldsw + _i * 8192), 16, 0, PG8_LOAD_AUX); } while (0)
; #define PG8_LDA(dst, b, h) do { _Pragma("unroll") for (int m = 0; m < 4; ++m) _Pragma("unroll") for (int k = 0; k < 2; ++k) dst[m][k] = *(const PG8_LAS bf16x8*)(lds + PG8_SA(b, h) + aoff + m * 2048 + k * 1024); } while (0)
; #define PG8_MMA(ai, bj, At, Bt) do { __builtin_amdgcn_s_setprio(1); _Pragma("unroll") for (int m = 0; m < 4; ++m) _Pragma("unroll") for (int n = 0; n < 2; ++n) _Pragma("unroll") for (int k = 0; k < 2; ++k) \
;         acc[ai][bj][m][n] = __builtin_amdgcn_mfma_f32_16x16x32_bf16(Bt[n][k], At[m][k], acc[ai][bj][m][n], 0, 0, 0); __builtin_amdgcn_s_setprio(0); } while (0)
; #define PG8_WAIT_V(n) asm volatile("s_waitcnt vmcnt(" #n ")" ::: "memory")
; #define PG8_WAIT_L(n) asm volatile("s_waitcnt lgkmcnt(" #n ")" ::: "memory")
; #define PG8_BAR __builtin_amdgcn_s_barrier()
; #define PG8_SCHED __builtin_amdgcn_sched_barrier(0)
;     __host__ __device__ bool next(int i, Unit& u) const {
;         const long L = (long)i * G + c; if (L >= nwg) return false;
;         int wgid = (int)L; { const int q = nwg / NXCD, r = nwg % NXCD, xcd = wgid % NXCD, off = wgid / NXCD; wgid = (xcd < r ? xcd * (q + 1) : r * (q + 1) + (xcd - r) * q) + off; }
;         const int nig = WGM * nN, gid = wgid / nig, fm = gid * WGM, gsz = (nM - fm) < WGM ? (nM - fm) : WGM;
;         u.pm = fm + ((wgid % nig) % gsz); u.pn = (wgid % nig) / gsz; return true;
; template <class Epi, class Sched, bool ALIGN_EPI = false, bool SP2 = false>
; __device__ __forceinline__ void gemm_phase(PG8_LAS unsigned char* lds, const Gemm g, const Sched& S, const Epi& E) {
;     ...
;             PG8_WAIT_V(8); PG8_WAIT_L(0); PG8_BAR; PG8_MMA(0, 0, At, B0); PG8_MMA(0, 1, At, B1); PG8_BAR; PG8_SCHED;
;             PG8_LDA(At, 0, 1); PG8_STAGE(PG8_SB(0, 0), b2, voffB); PG8_STAGE(PG8_SB(0, 1), b2 + hstepB, voffB); PG8_STAGE(PG8_SA(0, 0), a2, voffA);
;             PG8_WAIT_V(8); PG8_WAIT_L(0); PG8_BAR; PG8_MMA(1, 0, At, B0); PG8_MMA(1, 1, At, B1); PG8_BAR; PG8_SCHED;
	s_waitcnt lgkmcnt(0)
	v_mfma_f32_16x16x32_bf16 v[124:127], v[162:165], v[194:197], 0
	s_add_i32 s48, s48, 1
	s_mul_i32 s4, s48, s51
	v_mfma_f32_16x16x32_bf16 v[120:123], v[170:173], v[194:197], 0
	s_mul_hi_u32 s5, s48, s52
	s_add_i32 s5, s5, s4
	v_mfma_f32_16x16x32_bf16 v[108:111], v[162:165], v[202:205], 0
	s_mul_i32 s4, s48, s52
	v_readlane_b32 s15, v239, 0
	v_mfma_f32_16x16x32_bf16 v[104:107], v[170:173], v[202:205], 0
	s_add_u32 s18, s4, s15
	s_addc_u32 s19, s5, s42
	v_mfma_f32_16x16x32_bf16 v[92:95], v[162:165], v[210:213], 0
	s_cmp_lt_u32 s18, 0x900
	s_cselect_b64 s[4:5], -1, 0
	v_mfma_f32_16x16x32_bf16 v[88:91], v[170:173], v[210:213], 0
	s_ashr_i32 s14, s18, 31
	s_lshr_b32 s14, s14, 29
	v_mfma_f32_16x16x32_bf16 v[76:79], v[162:165], v[218:221], 0
	s_add_i32 s14, s18, s14
	s_ashr_i32 s15, s14, 3
	v_mfma_f32_16x16x32_bf16 v[72:75], v[170:173], v[218:221], 0
	s_and_b32 s14, s14, -8
	s_sub_i32 s14, s18, s14
	v_mfma_f32_16x16x32_bf16 v[124:127], v[166:169], v[198:201], v[124:127]
	s_cmp_lt_i32 s14, 0
	s_cselect_b32 s16, s43, 0x120
	v_mfma_f32_16x16x32_bf16 v[120:123], v[174:177], v[198:201], v[120:123]
	s_mul_i32 s14, s14, s16
	s_add_i32 s14, s14, s15
	v_mfma_f32_16x16x32_bf16 v[108:111], v[166:169], v[206:209], v[108:111]
	s_mul_hi_i32 s15, s14, 0x38e38e39
	s_lshr_b32 s16, s15, 31
	v_mfma_f32_16x16x32_bf16 v[104:107], v[174:177], v[206:209], v[104:107]
	s_ashr_i32 s15, s15, 5
	s_add_i32 s15, s15, s16
	v_mfma_f32_16x16x32_bf16 v[92:95], v[166:169], v[214:217], v[92:95]
	s_lshl_b32 s16, s15, 2
	s_sub_i32 s17, 64, s16
	v_mfma_f32_16x16x32_bf16 v[88:91], v[174:177], v[214:217], v[88:91]
	s_min_i32 s17, s17, 4
	s_mulk_i32 s15, 0x90
	v_mfma_f32_16x16x32_bf16 v[76:79], v[166:169], v[222:225], v[76:79]
	s_sub_i32 s15, s14, s15
	s_lshr_b32 s14, s15, 2
	v_mfma_f32_16x16x32_bf16 v[72:75], v[174:177], v[222:225], v[72:75]
	s_and_b32 s15, s15, 3
	s_add_i32 s16, s16, s15
	v_mfma_f32_16x16x32_bf16 v[116:119], v[178:181], v[194:197], 0
	s_ashr_i32 s17, s16, 31
	s_lshl_b64 s[18:19], s[16:17], 19
	v_mfma_f32_16x16x32_bf16 v[112:115], v[186:189], v[194:197], 0
	s_add_u32 s18, s33, s18
	s_addc_u32 s19, s36, s19
	v_mfma_f32_16x16x32_bf16 v[100:103], v[178:181], v[202:205], 0
	s_sub_u32 s98, s20, 0x40080
	s_subb_u32 s99, s21, 0
	v_mfma_f32_16x16x32_bf16 v[96:99], v[186:189], v[202:205], 0
	s_cmp_lg_u64 s[4:5], 0
	s_cselect_b32 s17, s19, s99
	v_mfma_f32_16x16x32_bf16 v[84:87], v[178:181], v[210:213], 0
	s_cselect_b32 s24, s18, s98
	s_ashr_i32 s15, s14, 31
	v_mfma_f32_16x16x32_bf16 v[80:83], v[186:189], v[210:213], 0
	s_lshl_b64 s[98:99], s[14:15], 19
	s_add_u32 s40, s64, s98
	v_mfma_f32_16x16x32_bf16 v[68:71], v[178:181], v[218:221], 0
	s_addc_u32 s41, s65, s99
	s_sub_u32 s98, s26, 0x100
	v_mfma_f32_16x16x32_bf16 v[64:67], v[186:189], v[218:221], 0
	s_subb_u32 s99, s27, 0
	s_cmp_lg_u64 s[4:5], 0
	v_mfma_f32_16x16x32_bf16 v[116:119], v[182:185], v[198:201], v[116:119]
	s_cselect_b32 s15, s41, s99
	s_cselect_b32 s25, s40, s98
	v_mfma_f32_16x16x32_bf16 v[112:115], v[190:193], v[198:201], v[112:115]
	v_mfma_f32_16x16x32_bf16 v[100:103], v[182:185], v[206:209], v[100:103]
	v_mfma_f32_16x16x32_bf16 v[96:99], v[190:193], v[206:209], v[96:99]
	v_mfma_f32_16x16x32_bf16 v[84:87], v[182:185], v[214:217], v[84:87]
	v_mfma_f32_16x16x32_bf16 v[80:83], v[190:193], v[214:217], v[80:83]
	v_mfma_f32_16x16x32_bf16 v[68:71], v[182:185], v[222:225], v[68:71]
	v_mfma_f32_16x16x32_bf16 v[64:67], v[190:193], v[222:225], v[64:67]
	s_barrier
	s_add_i32 s29, s53, s37
	v_lshl_add_u64 v[226:227], s[22:23], 0, v[132:133]
	s_mov_b32 m0, s29
	ds_read_b128 v[194:197], v161 offset:16384
	ds_read_b128 v[198:201], v161 offset:17408
	ds_read_b128 v[202:205], v161 offset:18432
	ds_read_b128 v[206:209], v161 offset:19456
	ds_read_b128 v[210:213], v161 offset:20480
	ds_read_b128 v[214:217], v161 offset:21504
	ds_read_b128 v[218:221], v161 offset:22528
	ds_read_b128 v[222:225], v161 offset:23552
	global_load_lds_dwordx4 v[226:227], off
	s_add_i32 m0, s29, 0x2000
	s_add_u32 s30, s22, 0x10000
	v_lshl_add_u64 v[228:229], s[22:23], 0, v[128:129]
	s_addc_u32 s31, s23, 0
	s_add_i32 s29, s54, s37
	global_load_lds_dwordx4 v[228:229], off
	v_lshl_add_u64 v[230:231], s[30:31], 0, v[132:133]
	s_mov_b32 m0, s29
	v_lshl_add_u64 v[232:233], s[34:35], 0, v[130:131]
	global_load_lds_dwordx4 v[230:231], off
	v_lshl_add_u64 v[230:231], s[30:31], 0, v[128:129]
	s_add_i32 m0, s29, 0x2000
	s_nop 0
	global_load_lds_dwordx4 v[230:231], off
	v_lshl_add_u64 v[230:231], s[34:35], 0, v[134:135]
	s_mov_b32 m0, s44
	s_nop 0
	global_load_lds_dwordx4 v[230:231], off
	s_mov_b32 m0, s45
	s_nop 0
	global_load_lds_dwordx4 v[232:233], off
	s_waitcnt vmcnt(8)
	s_waitcnt lgkmcnt(0)
	s_barrier
	s_waitcnt lgkmcnt(0)
	v_mfma_f32_16x16x32_bf16 v[60:63], v[162:165], v[194:197], 0
	v_mfma_f32_16x16x32_bf16 v[56:59], v[170:173], v[194:197], 0
	v_mfma_f32_16x16x32_bf16 v[44:47], v[162:165], v[202:205], 0
	v_mfma_f32_16x16x32_bf16 v[40:43], v[170:173], v[202:205], 0
	v_mfma_f32_16x16x32_bf16 v[28:31], v[162:165], v[210:213], 0
	v_mfma_f32_16x16x32_bf16 v[24:27], v[170:173], v[210:213], 0
	v_mfma_f32_16x16x32_bf16 v[12:15], v[162:165], v[218:221], 0
	v_mfma_f32_16x16x32_bf16 v[8:11], v[170:173], v[218:221], 0
	v_mfma_f32_16x16x32_bf16 v[60:63], v[166:169], v[198:201], v[60:63]
	v_mfma_f32_16x16x32_bf16 v[56:59], v[174:177], v[198:201], v[56:59]
	v_mfma_f32_16x16x32_bf16 v[44:47], v[166:169], v[206:209], v[44:47]
	v_mfma_f32_16x16x32_bf16 v[40:43], v[174:177], v[206:209], v[40:43]
	v_mfma_f32_16x16x32_bf16 v[28:31], v[166:169], v[214:217], v[28:31]
	v_mfma_f32_16x16x32_bf16 v[24:27], v[174:177], v[214:217], v[24:27]
	v_mfma_f32_16x16x32_bf16 v[12:15], v[166:169], v[222:225], v[12:15]
	v_mfma_f32_16x16x32_bf16 v[8:11], v[174:177], v[222:225], v[8:11]
	v_mfma_f32_16x16x32_bf16 v[52:55], v[178:181], v[194:197], 0
	v_mfma_f32_16x16x32_bf16 v[48:51], v[186:189], v[194:197], 0
	v_mfma_f32_16x16x32_bf16 v[36:39], v[178:181], v[202:205], 0
	v_mfma_f32_16x16x32_bf16 v[32:35], v[186:189], v[202:205], 0
	v_mfma_f32_16x16x32_bf16 v[20:23], v[178:181], v[210:213], 0
	v_mfma_f32_16x16x32_bf16 v[16:19], v[186:189], v[210:213], 0
	v_mfma_f32_16x16x32_bf16 v[4:7], v[178:181], v[218:221], 0
	v_mfma_f32_16x16x32_bf16 v[0:3], v[186:189], v[218:221], 0
	v_mfma_f32_16x16x32_bf16 v[52:55], v[182:185], v[198:201], v[52:55]
	v_mfma_f32_16x16x32_bf16 v[48:51], v[190:193], v[198:201], v[48:51]
	v_mfma_f32_16x16x32_bf16 v[36:39], v[182:185], v[206:209], v[36:39]
	v_mfma_f32_16x16x32_bf16 v[32:35], v[190:193], v[206:209], v[32:35]
	v_mfma_f32_16x16x32_bf16 v[20:23], v[182:185], v[214:217], v[20:23]
	v_mfma_f32_16x16x32_bf16 v[16:19], v[190:193], v[214:217], v[16:19]
	v_mfma_f32_16x16x32_bf16 v[4:7], v[182:185], v[222:225], v[4:7]
	v_mfma_f32_16x16x32_bf16 v[0:3], v[190:193], v[222:225], v[0:3]
	s_barrier
	s_branch .Lkmid_P3

; __device__ __forceinline__ unsigned swap8(unsigned v) { return (unsigned)__builtin_amdgcn_update_dpp(0, (int)v, 0x128  , 0xF, 0xF, false); }
; #define PG8_STAGE(bufoff, gbase, voff) do { _Pragma("unroll") for (int _i = 0; _i < 2; ++_i) \
;         __builtin_amdgcn_global_load_lds((const unsigned*)((const char*)(gbase) + (voff)[_i]), (PG8_LAS unsigned*)(lds + (bufoff) + ldsw + _i * 8192), 16, 0, PG8_LOAD_AUX); } while (0)
; #define PG8_LDA(dst, b, h) do { _Pragma("unroll") for (int m = 0; m < 4; ++m) _Pragma("unroll") for (int k = 0; k < 2; ++k) dst[m][k] = *(const PG8_LAS bf16x8*)(lds + PG8_SA(b, h) + aoff + m * 2048 + k * 1024); } while (0)
; #define PG8_LDB(dst, b, h) do { _Pragma("unroll") for (int n = 0; n < 2; ++n) _Pragma("unroll") for (int k = 0; k < 2; ++k) dst[n][k] = *(const PG8_LAS bf16x8*)(lds + PG8_SB(b, h) + boff + n * 2048 + k * 1024); } while (0)
; #define PG8_MMA(ai, bj, At, Bt) do { __builtin_amdgcn_s_setprio(1); _Pragma("unroll") for (int m = 0; m < 4; ++m) _Pragma("unroll") for (int n = 0; n < 2; ++n) _Pragma("unroll") for (int k = 0; k < 2; ++k) \
;         acc[ai][bj][m][n] = __builtin_amdgcn_mfma_f32_16x16x32_bf16(Bt[n][k], At[m][k], acc[ai][bj][m][n], 0, 0, 0); __builtin_amdgcn_s_setprio(0); } while (0)
; #define PG8_WAIT_V(n) asm volatile("s_waitcnt vmcnt(" #n ")" ::: "memory")
; #define PG8_WAIT_L(n) asm volatile("s_waitcnt lgkmcnt(" #n ")" ::: "memory")
; __device__ __forceinline__ void wide_store(bf16_t* O, int ldc, int rowg  , int col0  , int fr, u32x4 w0, u32x4 w1) {
;     const bool lo = fr < 8;
;     u32x4 snd = lo ? w1 : w0, rcv;
;     rcv.x = swap8(snd.x); rcv.y = swap8(snd.y); rcv.z = swap8(snd.z); rcv.w = swap8(snd.w);
;     const u32x4 first = lo ? w0 : rcv, second = lo ? rcv : w1;
;     bf16_t* p = O + (size_t)(rowg + (fr & 7)) * ldc + col0 + (lo ? 0 : 32);
;     __builtin_nontemporal_store(first, (u32x4*)p); __builtin_nontemporal_store(second, (u32x4*)(p + (size_t)8 * ldc));
; template <class Epi, class Sched, bool ALIGN_EPI = false, bool SP2 = false>
; __device__ __forceinline__ void gemm_phase(PG8_LAS unsigned char* lds, const Gemm g, const Sched& S, const Epi& E) {
;     ...
;             PG8_LDB(B0, 0, 0); PG8_LDB(B1, 0, 1); PG8_SCHED; PG8_LDA(At, 0, 0); PG8_STAGE(PG8_SA(1, 1), a1 + hstepA, voffA);
;             PG8_WAIT_V(8); PG8_WAIT_L(0); PG8_BAR; PG8_MMA(0, 0, At, B0); PG8_MMA(0, 1, At, B1); PG8_BAR; PG8_SCHED;
.LBB0_366:
	s_add_u32 s20, s20, 0x40080
	s_addc_u32 s21, s21, 0
	s_add_u32 s26, s22, 0x100
	s_addc_u32 s27, s23, 0
	s_mov_b32 s28, -2
	ds_read_b128 v[162:165], v159
	ds_read_b128 v[166:169], v159 offset:1024
	ds_read_b128 v[170:173], v159 offset:2048
	ds_read_b128 v[174:177], v159 offset:3072
	ds_read_b128 v[178:181], v160
	ds_read_b128 v[182:185], v160 offset:1024
	ds_read_b128 v[186:189], v160 offset:2048
	ds_read_b128 v[190:193], v160 offset:3072
	s_add_u32 s22, s20, 0xfffc0080
	s_addc_u32 s23, s21, -1
	s_cmp_eq_u32 s28, 12
	s_cselect_b32 s35, s17, s23
	s_cselect_b32 s34, s24, s22
	s_cselect_b32 s23, s15, s27
	s_cselect_b32 s22, s25, s26
	v_lshl_add_u64 v[226:227], s[20:21], 0, v[138:139]
	s_add_i32 m0, s44, 0xc000
	ds_read_b128 v[194:197], v161
	ds_read_b128 v[198:201], v161 offset:1024
	ds_read_b128 v[202:205], v161 offset:2048
	ds_read_b128 v[206:209], v161 offset:3072
	ds_read_b128 v[210:213], v161 offset:4096
	ds_read_b128 v[214:217], v161 offset:5120
	ds_read_b128 v[218:221], v161 offset:6144
	ds_read_b128 v[222:225], v161 offset:7168
	global_load_lds_dwordx4 v[226:227], off
	v_lshl_add_u64 v[226:227], s[20:21], 0, v[140:141]
	s_add_i32 m0, s44, 0xe000
	s_nop 0
	global_load_lds_dwordx4 v[226:227], off
	s_waitcnt vmcnt(8)
	s_waitcnt lgkmcnt(0)
	s_barrier
	s_waitcnt lgkmcnt(0)
	v_mfma_f32_16x16x32_bf16 v[124:127], v[162:165], v[194:197], 0
	s_add_i32 s48, s48, 1
	s_mul_i32 s4, s48, s51
	v_mfma_f32_16x16x32_bf16 v[120:123], v[170:173], v[194:197], 0
	s_mul_hi_u32 s5, s48, s52
	s_add_i32 s5, s5, s4
	v_mfma_f32_16x16x32_bf16 v[108:111], v[162:165], v[202:205], 0
	global_store_dwordx4 v[240:241], v[56:59], off nt
	s_mul_i32 s4, s48, s52
	v_readlane_b32 s15, v239, 0
	v_mfma_f32_16x16x32_bf16 v[104:107], v[170:173], v[202:205], 0
	s_add_u32 s18, s4, s15
	s_addc_u32 s19, s5, s42
	v_mfma_f32_16x16x32_bf16 v[92:95], v[162:165], v[210:213], 0
	s_cmp_lt_u32 s18, 0x900
	s_cselect_b64 s[4:5], -1, 0
	v_mfma_f32_16x16x32_bf16 v[88:91], v[170:173], v[210:213], 0
	global_store_dwordx4 v[242:243], v[48:51], off nt
	s_ashr_i32 s14, s18, 31
	s_lshr_b32 s14, s14, 29
	v_mfma_f32_16x16x32_bf16 v[76:79], v[162:165], v[218:221], 0
	s_add_i32 s14, s18, s14
	s_ashr_i32 s15, s14, 3
	v_mfma_f32_16x16x32_bf16 v[72:75], v[170:173], v[218:221], 0
	s_and_b32 s14, s14, -8
	s_sub_i32 s14, s18, s14
	v_mfma_f32_16x16x32_bf16 v[124:127], v[166:169], v[198:201], v[124:127]
	global_store_dwordx4 v[244:245], v[40:43], off nt
	s_cmp_lt_i32 s14, 0
	s_cselect_b32 s16, s43, 0x120
	v_mfma_f32_16x16x32_bf16 v[120:123], v[174:177], v[198:201], v[120:123]
	s_mul_i32 s14, s14, s16
	s_add_i32 s14, s14, s15
	v_mfma_f32_16x16x32_bf16 v[108:111], v[166:169], v[206:209], v[108:111]
	s_mul_hi_i32 s15, s14, 0x38e38e39
	s_lshr_b32 s16, s15, 31
	v_mfma_f32_16x16x32_bf16 v[104:107], v[174:177], v[206:209], v[104:107]
	global_store_dwordx4 v[246:247], v[32:35], off nt
	s_ashr_i32 s15, s15, 5
	s_add_i32 s15, s15, s16
	v_mfma_f32_16x16x32_bf16 v[92:95], v[166:169], v[214:217], v[92:95]
	s_lshl_b32 s16, s15, 2
	s_sub_i32 s17, 64, s16
	v_mfma_f32_16x16x32_bf16 v[88:91], v[174:177], v[214:217], v[88:91]
	s_min_i32 s17, s17, 4
	s_mulk_i32 s15, 0x90
	v_mfma_f32_16x16x32_bf16 v[76:79], v[166:169], v[222:225], v[76:79]
	global_store_dwordx4 v[248:249], v[24:27], off nt
	s_sub_i32 s15, s14, s15
	s_lshr_b32 s14, s15, 2
	v_mfma_f32_16x16x32_bf16 v[72:75], v[174:177], v[222:225], v[72:75]
	s_and_b32 s15, s15, 3
	s_add_i32 s16, s16, s15
	v_mfma_f32_16x16x32_bf16 v[116:119], v[178:181], v[194:197], 0
	s_ashr_i32 s17, s16, 31
	s_lshl_b64 s[18:19], s[16:17], 19
	v_mfma_f32_16x16x32_bf16 v[112:115], v[186:189], v[194:197], 0
	global_store_dwordx4 v[250:251], v[16:19], off nt
	s_add_u32 s18, s33, s18
	s_addc_u32 s19, s36, s19
	v_mfma_f32_16x16x32_bf16 v[100:103], v[178:181], v[202:205], 0
	s_sub_u32 s98, s20, 0x40080
	s_subb_u32 s99, s21, 0
	v_mfma_f32_16x16x32_bf16 v[96:99], v[186:189], v[202:205], 0
	s_cmp_lg_u64 s[4:5], 0
	s_cselect_b32 s17, s19, s99
	v_mfma_f32_16x16x32_bf16 v[84:87], v[178:181], v[210:213], 0
	global_store_dwordx4 v[252:253], v[8:11], off nt
	s_cselect_b32 s24, s18, s98
	s_ashr_i32 s15, s14, 31
	v_mfma_f32_16x16x32_bf16 v[80:83], v[186:189], v[210:213], 0
	s_lshl_b64 s[98:99], s[14:15], 19
	s_add_u32 s40, s64, s98
	v_mfma_f32_16x16x32_bf16 v[68:71], v[178:181], v[218:221], 0
	s_addc_u32 s41, s65, s99
	s_sub_u32 s98, s26, 0x100
	v_mfma_f32_16x16x32_bf16 v[64:67], v[186:189], v[218:221], 0
	global_store_dwordx4 v[254:255], v[0:3], off nt
	s_subb_u32 s99, s27, 0
	s_cmp_lg_u64 s[4:5], 0
	v_mfma_f32_16x16x32_bf16 v[116:119], v[182:185], v[198:201], v[116:119]
	s_cselect_b32 s15, s41, s99
	s_cselect_b32 s25, s40, s98
	v_mfma_f32_16x16x32_bf16 v[112:115], v[190:193], v[198:201], v[112:115]
	v_mfma_f32_16x16x32_bf16 v[100:103], v[182:185], v[206:209], v[100:103]
	v_mfma_f32_16x16x32_bf16 v[96:99], v[190:193], v[206:209], v[96:99]
	v_mfma_f32_16x16x32_bf16 v[84:87], v[182:185], v[214:217], v[84:87]
	v_mfma_f32_16x16x32_bf16 v[80:83], v[190:193], v[214:217], v[80:83]
	v_mfma_f32_16x16x32_bf16 v[68:71], v[182:185], v[222:225], v[68:71]
	v_mfma_f32_16x16x32_bf16 v[64:67], v[190:193], v[222:225], v[64:67]
	s_barrier
; #define PG8_STAGE(bufoff, gbase, voff) do { _Pragma("unroll") for (int _i = 0; _i < 2; ++_i) \
;         __builtin_amdgcn_global_load_lds((const unsigned*)((const char*)(gbase) + (voff)[_i]), (PG8_LAS unsigned*)(lds + (bufoff) + ldsw + _i * 8192), 16, 0, PG8_LOAD_AUX); } while (0)
; #define PG8_LDA(dst, b, h) do { _Pragma("unroll") for (int m = 0; m < 4; ++m) _Pragma("unroll") for (int k = 0; k < 2; ++k) dst[m][k] = *(const PG8_LAS bf16x8*)(lds + PG8_SA(b, h) + aoff + m * 2048 + k * 1024); } while (0)
; #define PG8_MMA(ai, bj, At, Bt) do { __builtin_amdgcn_s_setprio(1); _Pragma("unroll") for (int m = 0; m < 4; ++m) _Pragma("unroll") for (int n = 0; n < 2; ++n) _Pragma("unroll") for (int k = 0; k < 2; ++k) \
;         acc[ai][bj][m][n] = __builtin_amdgcn_mfma_f32_16x16x32_bf16(Bt[n][k], At[m][k], acc[ai][bj][m][n], 0, 0, 0); __builtin_amdgcn_s_setprio(0); } while (0)
; #define PG8_WAIT_V(n) asm volatile("s_waitcnt vmcnt(" #n ")" ::: "memory")
; #define PG8_WAIT_L(n) asm volatile("s_waitcnt lgkmcnt(" #n ")" ::: "memory")
; #define PG8_BAR __builtin_amdgcn_s_barrier()
; #define PG8_SCHED __builtin_amdgcn_sched_barrier(0)
; template <class Epi, class Sched, bool ALIGN_EPI = false, bool SP2 = false>
; __device__ __forceinline__ void gemm_phase(PG8_LAS unsigned char* lds, const Gemm g, const Sched& S, const Epi& E) {
;     ...
;             PG8_LDA(At, 0, 1); PG8_STAGE(PG8_SB(0, 0), b2, voffB); PG8_STAGE(PG8_SB(0, 1), b2 + hstepB, voffB); PG8_STAGE(PG8_SA(0, 0), a2, voffA);
;             PG8_WAIT_V(8); PG8_WAIT_L(0); PG8_BAR; PG8_MMA(1, 0, At, B0); PG8_MMA(1, 1, At, B1); PG8_BAR; PG8_SCHED;
	s_add_i32 s29, s53, s37
	v_lshl_add_u64 v[226:227], s[22:23], 0, v[132:133]
	s_mov_b32 m0, s29
	ds_read_b128 v[194:197], v161 offset:16384
	ds_read_b128 v[198:201], v161 offset:17408
	ds_read_b128 v[202:205], v161 offset:18432
	ds_read_b128 v[206:209], v161 offset:19456
	ds_read_b128 v[210:213], v161 offset:20480
	ds_read_b128 v[214:217], v161 offset:21504
	ds_read_b128 v[218:221], v161 offset:22528
	ds_read_b128 v[222:225], v161 offset:23552
	global_load_lds_dwordx4 v[226:227], off
	s_add_i32 m0, s29, 0x2000
	s_add_u32 s30, s22, 0x10000
	v_lshl_add_u64 v[228:229], s[22:23], 0, v[128:129]
	s_addc_u32 s31, s23, 0
	s_add_i32 s29, s54, s37
	global_load_lds_dwordx4 v[228:229], off
	v_lshl_add_u64 v[230:231], s[30:31], 0, v[132:133]
	s_mov_b32 m0, s29
	v_lshl_add_u64 v[232:233], s[34:35], 0, v[130:131]
	global_load_lds_dwordx4 v[230:231], off
	v_lshl_add_u64 v[230:231], s[30:31], 0, v[128:129]
	s_add_i32 m0, s29, 0x2000
	s_nop 0
	global_load_lds_dwordx4 v[230:231], off
	v_lshl_add_u64 v[230:231], s[34:35], 0, v[134:135]
	s_mov_b32 m0, s44
	s_nop 0
	global_load_lds_dwordx4 v[230:231], off
	s_mov_b32 m0, s45
	s_nop 0
	global_load_lds_dwordx4 v[232:233], off
	s_waitcnt vmcnt(16)
	s_waitcnt lgkmcnt(0)
	s_barrier
	s_waitcnt lgkmcnt(0)
	v_mfma_f32_16x16x32_bf16 v[60:63], v[162:165], v[194:197], 0
	v_mfma_f32_16x16x32_bf16 v[56:59], v[170:173], v[194:197], 0
	v_mfma_f32_16x16x32_bf16 v[44:47], v[162:165], v[202:205], 0
	v_mfma_f32_16x16x32_bf16 v[40:43], v[170:173], v[202:205], 0
	v_mfma_f32_16x16x32_bf16 v[28:31], v[162:165], v[210:213], 0
	v_mfma_f32_16x16x32_bf16 v[24:27], v[170:173], v[210:213], 0
	v_mfma_f32_16x16x32_bf16 v[12:15], v[162:165], v[218:221], 0
	v_mfma_f32_16x16x32_bf16 v[8:11], v[170:173], v[218:221], 0
	v_mfma_f32_16x16x32_bf16 v[60:63], v[166:169], v[198:201], v[60:63]
	v_mfma_f32_16x16x32_bf16 v[56:59], v[174:177], v[198:201], v[56:59]
	v_mfma_f32_16x16x32_bf16 v[44:47], v[166:169], v[206:209], v[44:47]
	v_mfma_f32_16x16x32_bf16 v[40:43], v[174:177], v[206:209], v[40:43]
	v_mfma_f32_16x16x32_bf16 v[28:31], v[166:169], v[214:217], v[28:31]
	v_mfma_f32_16x16x32_bf16 v[24:27], v[174:177], v[214:217], v[24:27]
	v_mfma_f32_16x16x32_bf16 v[12:15], v[166:169], v[222:225], v[12:15]
	v_mfma_f32_16x16x32_bf16 v[8:11], v[174:177], v[222:225], v[8:11]
	v_mfma_f32_16x16x32_bf16 v[52:55], v[178:181], v[194:197], 0
	v_mfma_f32_16x16x32_bf16 v[48:51], v[186:189], v[194:197], 0
	v_mfma_f32_16x16x32_bf16 v[36:39], v[178:181], v[202:205], 0
	v_mfma_f32_16x16x32_bf16 v[32:35], v[186:189], v[202:205], 0
	v_mfma_f32_16x16x32_bf16 v[20:23], v[178:181], v[210:213], 0
	v_mfma_f32_16x16x32_bf16 v[16:19], v[186:189], v[210:213], 0
	v_mfma_f32_16x16x32_bf16 v[4:7], v[178:181], v[218:221], 0
	v_mfma_f32_16x16x32_bf16 v[0:3], v[186:189], v[218:221], 0
	v_mfma_f32_16x16x32_bf16 v[52:55], v[182:185], v[198:201], v[52:55]
	v_mfma_f32_16x16x32_bf16 v[48:51], v[190:193], v[198:201], v[48:51]
	v_mfma_f32_16x16x32_bf16 v[36:39], v[182:185], v[206:209], v[36:39]
	v_mfma_f32_16x16x32_bf16 v[32:35], v[190:193], v[206:209], v[32:35]
	v_mfma_f32_16x16x32_bf16 v[20:23], v[182:185], v[214:217], v[20:23]
	v_mfma_f32_16x16x32_bf16 v[16:19], v[190:193], v[214:217], v[16:19]
	v_mfma_f32_16x16x32_bf16 v[4:7], v[182:185], v[222:225], v[4:7]
	v_mfma_f32_16x16x32_bf16 v[0:3], v[190:193], v[222:225], v[0:3]
	s_barrier
	s_branch .Lkmid_P3

; __device__ __forceinline__ unsigned cvt_pk_bf16(float lo, float hi) { const cvt_f32x2_t v = {lo, hi}; const cvt_bf16x2_t b = __builtin_convertvector(v, cvt_bf16x2_t); return __builtin_bit_cast(unsigned, b); }
; __device__ __forceinline__ unsigned swap8(unsigned v) { return (unsigned)__builtin_amdgcn_update_dpp(0, (int)v, 0x128  , 0xF, 0xF, false); }
; __device__ __forceinline__ void wide_store(bf16_t* O, int ldc, int rowg  , int col0  , int fr, u32x4 w0, u32x4 w1) {
;     const bool lo = fr < 8;
;     u32x4 snd = lo ? w1 : w0, rcv;
;     rcv.x = swap8(snd.x); rcv.y = swap8(snd.y); rcv.z = swap8(snd.z); rcv.w = swap8(snd.w);
;     const u32x4 first = lo ? w0 : rcv, second = lo ? rcv : w1;
;     bf16_t* p = O + (size_t)(rowg + (fr & 7)) * ldc + col0 + (lo ? 0 : 32);
;     __builtin_nontemporal_store(first, (u32x4*)p); __builtin_nontemporal_store(second, (u32x4*)(p + (size_t)8 * ldc));
; }
;     __device__ __forceinline__ void operator()(const f32x4 (&acc)[2][2][4][2], const Unit& u, int wr, int wc, int fr, int fq) const {
;         const int col0 = u.pn * BM + wc * 64 + 8 * fq;
; #pragma unroll
;         for (int ai = 0; ai < 2; ++ai)
; #pragma unroll
;             for (int m = 0; m < 4; ++m) { const int rowg = u.pm * BM + ai * HALF + wr * 64 + m * 16;
;                 const float sc = slots ? rstd_from_slots(slots, rowg + fr, fq) : 1.0f;
;                 u32x4 w[2];
; #pragma unroll
;                 for (int bj = 0; bj < 2; ++bj) { const f32x4 v0 = acc[ai][bj][m][0] * sc, v1 = acc[ai][bj][m][1] * sc;
;                     w[bj].x = cvt_pk_bf16(v0[0], v0[1]); w[bj].y = cvt_pk_bf16(v0[2], v0[3]); w[bj].z = cvt_pk_bf16(v1[0], v1[1]); w[bj].w = cvt_pk_bf16(v1[2], v1[3]); }
;                 wide_store(O, ldc, rowg, col0, fr, w[0], w[1]); }
.LBB0_372:
	v_readlane_b32 s30, v239, 49
	v_readlane_b32 s31, v239, 50
	s_lshl_b32 s0, s0, 8
	v_lshl_or_b32 v162, s1, 8, v147
	v_add_u32_e32 v164, s0, v148
	v_ashrrev_i32_e32 v163, 31, v162
	s_mov_b32 s98, 0x24000
	s_mov_b32 s99, 0
	v_lshlrev_b64 v[162:163], 1, v[162:163]
	v_mov_b64_e32 v[168:169], s[30:31]
	v_mad_i64_i32 v[164:165], s[20:21], v164, s55, v[168:169]
	v_lshl_add_u64 v[162:163], v[162:163], 0, v[136:137]
	v_lshl_add_u64 v[164:165], v[164:165], 0, v[162:163]
	v_cvt_pk_bf16_f32 v124, v124, v125
	v_cvt_pk_bf16_f32 v125, v126, v127
	v_cvt_pk_bf16_f32 v126, v120, v121
	v_cvt_pk_bf16_f32 v127, v122, v123
	v_cvt_pk_bf16_f32 v116, v116, v117
	v_cvt_pk_bf16_f32 v117, v118, v119
	v_cvt_pk_bf16_f32 v118, v112, v113
	v_cvt_pk_bf16_f32 v119, v114, v115
	v_cvt_pk_bf16_f32 v108, v108, v109
	v_cvt_pk_bf16_f32 v109, v110, v111
	v_cvt_pk_bf16_f32 v110, v104, v105
	v_cvt_pk_bf16_f32 v111, v106, v107
	v_cvt_pk_bf16_f32 v100, v100, v101
	v_cvt_pk_bf16_f32 v101, v102, v103
	v_cvt_pk_bf16_f32 v102, v96, v97
	v_cvt_pk_bf16_f32 v103, v98, v99
	s_not_b64 vcc, s[2:3]
	v_cndmask_b32_dpp v112, v124, v116, vcc row_ror:8 row_mask:0xf bank_mask:0xf
	v_cndmask_b32_dpp v113, v125, v117, vcc row_ror:8 row_mask:0xf bank_mask:0xf
	v_cndmask_b32_dpp v114, v126, v118, vcc row_ror:8 row_mask:0xf bank_mask:0xf
	v_cndmask_b32_dpp v115, v127, v119, vcc row_ror:8 row_mask:0xf bank_mask:0xf
	v_cndmask_b32_dpp v96, v108, v100, vcc row_ror:8 row_mask:0xf bank_mask:0xf
	v_cndmask_b32_dpp v97, v109, v101, vcc row_ror:8 row_mask:0xf bank_mask:0xf
	v_cndmask_b32_dpp v98, v110, v102, vcc row_ror:8 row_mask:0xf bank_mask:0xf
	v_cndmask_b32_dpp v99, v111, v103, vcc row_ror:8 row_mask:0xf bank_mask:0xf
	s_mov_b64 vcc, s[2:3]
	v_cndmask_b32_dpp v120, v116, v124, vcc row_ror:8 row_mask:0xf bank_mask:0xf
	v_cndmask_b32_dpp v121, v117, v125, vcc row_ror:8 row_mask:0xf bank_mask:0xf
	v_cndmask_b32_dpp v122, v118, v126, vcc row_ror:8 row_mask:0xf bank_mask:0xf
	v_cndmask_b32_dpp v123, v119, v127, vcc row_ror:8 row_mask:0xf bank_mask:0xf
	v_cndmask_b32_dpp v104, v100, v108, vcc row_ror:8 row_mask:0xf bank_mask:0xf
	v_cndmask_b32_dpp v105, v101, v109, vcc row_ror:8 row_mask:0xf bank_mask:0xf
	v_cndmask_b32_dpp v106, v102, v110, vcc row_ror:8 row_mask:0xf bank_mask:0xf
	v_cndmask_b32_dpp v107, v103, v111, vcc row_ror:8 row_mask:0xf bank_mask:0xf
	global_store_dwordx4 v[164:165], v[120:123], off nt
	v_lshl_add_u64 v[166:167], v[164:165], 0, s[98:99]
	global_store_dwordx4 v[166:167], v[112:115], off nt
	v_lshl_add_u64 v[164:165], v[166:167], 0, s[98:99]
	global_store_dwordx4 v[164:165], v[104:107], off nt
	v_lshl_add_u64 v[166:167], v[164:165], 0, s[98:99]
	global_store_dwordx4 v[166:167], v[96:99], off nt
	v_cvt_pk_bf16_f32 v92, v92, v93
	v_cvt_pk_bf16_f32 v93, v94, v95
	v_cvt_pk_bf16_f32 v94, v88, v89
	v_cvt_pk_bf16_f32 v95, v90, v91
	v_cvt_pk_bf16_f32 v84, v84, v85
	v_cvt_pk_bf16_f32 v85, v86, v87
	v_cvt_pk_bf16_f32 v86, v80, v81
	v_cvt_pk_bf16_f32 v87, v82, v83
	v_cvt_pk_bf16_f32 v76, v76, v77
	v_cvt_pk_bf16_f32 v77, v78, v79
	v_cvt_pk_bf16_f32 v78, v72, v73
	v_cvt_pk_bf16_f32 v79, v74, v75
	v_cvt_pk_bf16_f32 v68, v68, v69
	v_cvt_pk_bf16_f32 v69, v70, v71
	v_cvt_pk_bf16_f32 v70, v64, v65
	v_cvt_pk_bf16_f32 v71, v66, v67
	s_not_b64 vcc, s[2:3]
	v_cndmask_b32_dpp v80, v92, v84, vcc row_ror:8 row_mask:0xf bank_mask:0xf
	v_cndmask_b32_dpp v81, v93, v85, vcc row_ror:8 row_mask:0xf bank_mask:0xf
	v_cndmask_b32_dpp v82, v94, v86, vcc row_ror:8 row_mask:0xf bank_mask:0xf
	v_cndmask_b32_dpp v83, v95, v87, vcc row_ror:8 row_mask:0xf bank_mask:0xf
	v_cndmask_b32_dpp v64, v76, v68, vcc row_ror:8 row_mask:0xf bank_mask:0xf
	v_cndmask_b32_dpp v65, v77, v69, vcc row_ror:8 row_mask:0xf bank_mask:0xf
	v_cndmask_b32_dpp v66, v78, v70, vcc row_ror:8 row_mask:0xf bank_mask:0xf
	v_cndmask_b32_dpp v67, v79, v71, vcc row_ror:8 row_mask:0xf bank_mask:0xf
	s_mov_b64 vcc, s[2:3]
	v_cndmask_b32_dpp v88, v84, v92, vcc row_ror:8 row_mask:0xf bank_mask:0xf
	v_cndmask_b32_dpp v89, v85, v93, vcc row_ror:8 row_mask:0xf bank_mask:0xf
	v_cndmask_b32_dpp v90, v86, v94, vcc row_ror:8 row_mask:0xf bank_mask:0xf
	v_cndmask_b32_dpp v91, v87, v95, vcc row_ror:8 row_mask:0xf bank_mask:0xf
	v_cndmask_b32_dpp v72, v68, v76, vcc row_ror:8 row_mask:0xf bank_mask:0xf
	v_cndmask_b32_dpp v73, v69, v77, vcc row_ror:8 row_mask:0xf bank_mask:0xf
	v_cndmask_b32_dpp v74, v70, v78, vcc row_ror:8 row_mask:0xf bank_mask:0xf
	v_cndmask_b32_dpp v75, v71, v79, vcc row_ror:8 row_mask:0xf bank_mask:0xf
	v_lshl_add_u64 v[164:165], v[166:167], 0, s[98:99]
	global_store_dwordx4 v[164:165], v[88:91], off nt
	v_lshl_add_u64 v[166:167], v[164:165], 0, s[98:99]
	global_store_dwordx4 v[166:167], v[80:83], off nt
; __device__ __forceinline__ unsigned cvt_pk_bf16(float lo, float hi) { const cvt_f32x2_t v = {lo, hi}; const cvt_bf16x2_t b = __builtin_convertvector(v, cvt_bf16x2_t); return __builtin_bit_cast(unsigned, b); }
; __device__ __forceinline__ unsigned swap8(unsigned v) { return (unsigned)__builtin_amdgcn_update_dpp(0, (int)v, 0x128  , 0xF, 0xF, false); }
; __device__ __forceinline__ void wide_store(bf16_t* O, int ldc, int rowg  , int col0  , int fr, u32x4 w0, u32x4 w1) {
;     const bool lo = fr < 8;
;     u32x4 snd = lo ? w1 : w0, rcv;
;     rcv.x = swap8(snd.x); rcv.y = swap8(snd.y); rcv.z = swap8(snd.z); rcv.w = swap8(snd.w);
;     const u32x4 first = lo ? w0 : rcv, second = lo ? rcv : w1;
;     bf16_t* p = O + (size_t)(rowg + (fr & 7)) * ldc + col0 + (lo ? 0 : 32);
;     __builtin_nontemporal_store(first, (u32x4*)p); __builtin_nontemporal_store(second, (u32x4*)(p + (size_t)8 * ldc));
; }
;     __device__ __forceinline__ void operator()(const f32x4 (&acc)[2][2][4][2], const Unit& u, int wr, int wc, int fr, int fq) const {
;     ...
;             for (int m = 0; m < 4; ++m) { const int rowg = u.pm * BM + ai * HALF + wr * 64 + m * 16;
;                 const float sc = slots ? rstd_from_slots(slots, rowg + fr, fq) : 1.0f;
;                 u32x4 w[2];
; #pragma unroll
;                 for (int bj = 0; bj < 2; ++bj) { const f32x4 v0 = acc[ai][bj][m][0] * sc, v1 = acc[ai][bj][m][1] * sc;
;                     w[bj].x = cvt_pk_bf16(v0[0], v0[1]); w[bj].y = cvt_pk_bf16(v0[2], v0[3]); w[bj].z = cvt_pk_bf16(v1[0], v1[1]); w[bj].w = cvt_pk_bf16(v1[2], v1[3]); }
;                 wide_store(O, ldc, rowg, col0, fr, w[0], w[1]); }
	v_lshl_add_u64 v[164:165], v[166:167], 0, s[98:99]
	global_store_dwordx4 v[164:165], v[72:75], off nt
	v_lshl_add_u64 v[166:167], v[164:165], 0, s[98:99]
	global_store_dwordx4 v[166:167], v[64:67], off nt
	v_cvt_pk_bf16_f32 v60, v60, v61
	v_cvt_pk_bf16_f32 v61, v62, v63
	v_cvt_pk_bf16_f32 v62, v56, v57
	v_cvt_pk_bf16_f32 v63, v58, v59
	v_cvt_pk_bf16_f32 v52, v52, v53
	v_cvt_pk_bf16_f32 v53, v54, v55
	v_cvt_pk_bf16_f32 v54, v48, v49
	v_cvt_pk_bf16_f32 v55, v50, v51
	v_cvt_pk_bf16_f32 v44, v44, v45
	v_cvt_pk_bf16_f32 v45, v46, v47
	v_cvt_pk_bf16_f32 v46, v40, v41
	v_cvt_pk_bf16_f32 v47, v42, v43
	v_cvt_pk_bf16_f32 v36, v36, v37
	v_cvt_pk_bf16_f32 v37, v38, v39
	v_cvt_pk_bf16_f32 v38, v32, v33
	v_cvt_pk_bf16_f32 v39, v34, v35
	s_not_b64 vcc, s[2:3]
	v_cndmask_b32_dpp v48, v60, v52, vcc row_ror:8 row_mask:0xf bank_mask:0xf
	v_cndmask_b32_dpp v49, v61, v53, vcc row_ror:8 row_mask:0xf bank_mask:0xf
	v_cndmask_b32_dpp v50, v62, v54, vcc row_ror:8 row_mask:0xf bank_mask:0xf
	v_cndmask_b32_dpp v51, v63, v55, vcc row_ror:8 row_mask:0xf bank_mask:0xf
	v_cndmask_b32_dpp v32, v44, v36, vcc row_ror:8 row_mask:0xf bank_mask:0xf
	v_cndmask_b32_dpp v33, v45, v37, vcc row_ror:8 row_mask:0xf bank_mask:0xf
	v_cndmask_b32_dpp v34, v46, v38, vcc row_ror:8 row_mask:0xf bank_mask:0xf
	v_cndmask_b32_dpp v35, v47, v39, vcc row_ror:8 row_mask:0xf bank_mask:0xf
	s_mov_b64 vcc, s[2:3]
	v_cndmask_b32_dpp v56, v52, v60, vcc row_ror:8 row_mask:0xf bank_mask:0xf
	v_cndmask_b32_dpp v57, v53, v61, vcc row_ror:8 row_mask:0xf bank_mask:0xf
	v_cndmask_b32_dpp v58, v54, v62, vcc row_ror:8 row_mask:0xf bank_mask:0xf
	v_cndmask_b32_dpp v59, v55, v63, vcc row_ror:8 row_mask:0xf bank_mask:0xf
	v_cndmask_b32_dpp v40, v36, v44, vcc row_ror:8 row_mask:0xf bank_mask:0xf
	v_cndmask_b32_dpp v41, v37, v45, vcc row_ror:8 row_mask:0xf bank_mask:0xf
	v_cndmask_b32_dpp v42, v38, v46, vcc row_ror:8 row_mask:0xf bank_mask:0xf
	v_cndmask_b32_dpp v43, v39, v47, vcc row_ror:8 row_mask:0xf bank_mask:0xf
	s_mov_b32 s98, 0x144000
	v_lshl_add_u64 v[240:241], v[166:167], 0, s[98:99]
	s_mov_b32 s98, 0x24000
	v_lshl_add_u64 v[242:243], v[240:241], 0, s[98:99]
	v_lshl_add_u64 v[244:245], v[242:243], 0, s[98:99]
	v_lshl_add_u64 v[246:247], v[244:245], 0, s[98:99]
	v_cvt_pk_bf16_f32 v28, v28, v29
	v_cvt_pk_bf16_f32 v29, v30, v31
	v_cvt_pk_bf16_f32 v30, v24, v25
	v_cvt_pk_bf16_f32 v31, v26, v27
	v_cvt_pk_bf16_f32 v20, v20, v21
	v_cvt_pk_bf16_f32 v21, v22, v23
	v_cvt_pk_bf16_f32 v22, v16, v17
	v_cvt_pk_bf16_f32 v23, v18, v19
	v_cvt_pk_bf16_f32 v12, v12, v13
	v_cvt_pk_bf16_f32 v13, v14, v15
	v_cvt_pk_bf16_f32 v14, v8, v9
	v_cvt_pk_bf16_f32 v15, v10, v11
	v_cvt_pk_bf16_f32 v4, v4, v5
	v_cvt_pk_bf16_f32 v5, v6, v7
	v_cvt_pk_bf16_f32 v6, v0, v1
	v_cvt_pk_bf16_f32 v7, v2, v3
	s_not_b64 vcc, s[2:3]
	v_cndmask_b32_dpp v16, v28, v20, vcc row_ror:8 row_mask:0xf bank_mask:0xf
	v_cndmask_b32_dpp v17, v29, v21, vcc row_ror:8 row_mask:0xf bank_mask:0xf
	v_cndmask_b32_dpp v18, v30, v22, vcc row_ror:8 row_mask:0xf bank_mask:0xf
	v_cndmask_b32_dpp v19, v31, v23, vcc row_ror:8 row_mask:0xf bank_mask:0xf
	v_cndmask_b32_dpp v0, v12, v4, vcc row_ror:8 row_mask:0xf bank_mask:0xf
	v_cndmask_b32_dpp v1, v13, v5, vcc row_ror:8 row_mask:0xf bank_mask:0xf
	v_cndmask_b32_dpp v2, v14, v6, vcc row_ror:8 row_mask:0xf bank_mask:0xf
	v_cndmask_b32_dpp v3, v15, v7, vcc row_ror:8 row_mask:0xf bank_mask:0xf
	s_mov_b64 vcc, s[2:3]
	v_cndmask_b32_dpp v24, v20, v28, vcc row_ror:8 row_mask:0xf bank_mask:0xf
	v_cndmask_b32_dpp v25, v21, v29, vcc row_ror:8 row_mask:0xf bank_mask:0xf
	v_cndmask_b32_dpp v26, v22, v30, vcc row_ror:8 row_mask:0xf bank_mask:0xf
	v_cndmask_b32_dpp v27, v23, v31, vcc row_ror:8 row_mask:0xf bank_mask:0xf
	v_cndmask_b32_dpp v8, v4, v12, vcc row_ror:8 row_mask:0xf bank_mask:0xf
	v_cndmask_b32_dpp v9, v5, v13, vcc row_ror:8 row_mask:0xf bank_mask:0xf
	v_cndmask_b32_dpp v10, v6, v14, vcc row_ror:8 row_mask:0xf bank_mask:0xf
	v_cndmask_b32_dpp v11, v7, v15, vcc row_ror:8 row_mask:0xf bank_mask:0xf
	v_lshl_add_u64 v[248:249], v[246:247], 0, s[98:99]
	v_lshl_add_u64 v[250:251], v[248:249], 0, s[98:99]
	v_lshl_add_u64 v[252:253], v[250:251], 0, s[98:99]
	v_lshl_add_u64 v[254:255], v[252:253], 0, s[98:99]
	s_andn2_b64 vcc, exec, s[4:5]
	s_mov_b64 s[0:1], -1
	s_cbranch_vccz .Lqkv_defer_372
	global_store_dwordx4 v[240:241], v[56:59], off nt
	global_store_dwordx4 v[242:243], v[48:51], off nt
	global_store_dwordx4 v[244:245], v[40:43], off nt
	global_store_dwordx4 v[246:247], v[32:35], off nt
	global_store_dwordx4 v[248:249], v[24:27], off nt
	global_store_dwordx4 v[250:251], v[16:19], off nt
	global_store_dwordx4 v[252:253], v[8:11], off nt
	global_store_dwordx4 v[254:255], v[0:3], off nt
